# FoX causal band steps hand-scheduled per wave (only visible sub-tiles computed, one triangular-masked tile) + T=40 skip threshold
# speedup vs baseline: 1.1950x; 1.0333x over previous
.LBB0_574:
	v_readfirstlane_b32 s2, v165
	s_nop 3
	s_lshr_b32 s2, s2, 6
	s_lshl_b32 s2, s2, 5
	s_lshl_b32 s3, s48, 8
	s_add_i32 s2, s2, s3
	s_add_i32 s20, s2, -32
	s_lshl_b32 s42, s20, 2
	s_mul_i32 s20, s20, 0x1e00
	s_add_u32 s20, s20, 0x7001200
	s_add_u32 s2, s28, s20
	s_addc_u32 s3, s29, 0
	v_and_b32_e32 v60, 31, v165
	v_mul_u32_u24_e32 v60, 0x1e00, v60
	v_bfe_u32 v61, v165, 5, 1
	v_lshl_add_u32 v60, v61, 4, v60
	v_add_u32_e32 v61, s42, v179
	global_load_dwordx4 v[64:67], v60, s[2:3] offset:0
	global_load_dwordx4 v[68:71], v60, s[2:3] offset:32
	global_load_dwordx4 v[72:75], v60, s[2:3] offset:64
	global_load_dwordx4 v[76:79], v60, s[2:3] offset:96
	ds_read_b128 v[32:35], v61
	ds_read_b128 v[36:39], v61 offset:32
	ds_read_b128 v[40:43], v61 offset:64
	ds_read_b128 v[44:47], v61 offset:96
	s_waitcnt lgkmcnt(0)
	s_waitcnt vmcnt(3)
	v_mfma_f32_32x32x16_bf16 v[32:47], v[64:67], v[96:99], v[32:47]
	s_waitcnt vmcnt(2)
	v_mfma_f32_32x32x16_bf16 v[32:47], v[68:71], v[100:103], v[32:47]
	s_waitcnt vmcnt(1)
	v_mfma_f32_32x32x16_bf16 v[32:47], v[72:75], v[104:107], v[32:47]
	s_waitcnt vmcnt(0)
	v_mfma_f32_32x32x16_bf16 v[32:47], v[76:79], v[108:111], v[32:47]
	s_nop 11
	v_max3_f32 v222, v32, v33, v34
	v_max3_f32 v222, v222, v35, v36
	v_max3_f32 v222, v222, v37, v38
	v_max3_f32 v222, v222, v39, v40
	v_max3_f32 v222, v222, v41, v42
	v_max3_f32 v222, v222, v43, v44
	v_max3_f32 v222, v222, v45, v46
	v_max_f32_e32 v222, v222, v47
	ds_bpermute_b32 v183, v180, v222
	s_waitcnt lgkmcnt(0)
	v_max_f32_e32 v183, v183, v183
	v_max_f32_e32 v182, v222, v183
	v_sub_f32_e32 v182, v182, v161
	v_add_f32_e32 v255, 0xc2200000, v182
	s_cmp_lt_u32 s48, 8
	s_cbranch_scc1 .Lfox_kpass_done
	s_mov_b64 s[2:3], 0x7001200
	v_lshl_add_u64 v[202:203], v[158:159], 0, s[2:3]
	s_mov_b64 s[2:3], 0x78000
	v_lshl_add_u64 v[204:205], v[202:203], 0, s[2:3]
	v_mov_b32_e32 v210, 0
	s_lshl_b32 s20, s48, 1
	s_add_i32 s100, s20, 1
	s_add_i32 s20, s48, 1
	s_lshr_b32 s20, s20, 1
	s_mov_b32 s101, 0
	s_mov_b32 s3, 0
	s_min_u32 s2, s101, s100
	s_mul_i32 s2, s2, 0xf0000
	s_add_i32 s101, s101, 1
	v_lshl_add_u64 v[206:207], v[202:203], 0, s[2:3]
	v_lshl_add_u64 v[208:209], v[204:205], 0, s[2:3]
	global_load_dwordx4 v[32:35], v[206:207], off
	global_load_dwordx4 v[36:39], v[208:209], off
	s_min_u32 s2, s101, s100
	s_mul_i32 s2, s2, 0xf0000
	s_add_i32 s101, s101, 1
	v_lshl_add_u64 v[206:207], v[202:203], 0, s[2:3]
	v_lshl_add_u64 v[208:209], v[204:205], 0, s[2:3]
	global_load_dwordx4 v[40:43], v[206:207], off
	global_load_dwordx4 v[44:47], v[208:209], off
	s_min_u32 s2, s101, s100
	s_mul_i32 s2, s2, 0xf0000
	s_add_i32 s101, s101, 1
	v_lshl_add_u64 v[206:207], v[202:203], 0, s[2:3]
	v_lshl_add_u64 v[208:209], v[204:205], 0, s[2:3]
	global_load_dwordx4 v[48:51], v[206:207], off
	global_load_dwordx4 v[52:55], v[208:209], off
	s_min_u32 s2, s101, s100
	s_mul_i32 s2, s2, 0xf0000
	s_add_i32 s101, s101, 1
	v_lshl_add_u64 v[206:207], v[202:203], 0, s[2:3]
	v_lshl_add_u64 v[208:209], v[204:205], 0, s[2:3]
	global_load_dwordx4 v[56:59], v[206:207], off
	global_load_dwordx4 v[60:63], v[208:209], off
	s_min_u32 s2, s101, s100
	s_mul_i32 s2, s2, 0xf0000
	s_add_i32 s101, s101, 1
	v_lshl_add_u64 v[206:207], v[202:203], 0, s[2:3]
	v_lshl_add_u64 v[208:209], v[204:205], 0, s[2:3]
	global_load_dwordx4 v[64:67], v[206:207], off
	global_load_dwordx4 v[68:71], v[208:209], off
	s_min_u32 s2, s101, s100
	s_mul_i32 s2, s2, 0xf0000
	s_add_i32 s101, s101, 1
	v_lshl_add_u64 v[206:207], v[202:203], 0, s[2:3]
	v_lshl_add_u64 v[208:209], v[204:205], 0, s[2:3]
	global_load_dwordx4 v[72:75], v[206:207], off
	global_load_dwordx4 v[76:79], v[208:209], off
	s_min_u32 s2, s101, s100
	s_mul_i32 s2, s2, 0xf0000
	s_add_i32 s101, s101, 1
	v_lshl_add_u64 v[206:207], v[202:203], 0, s[2:3]
	v_lshl_add_u64 v[208:209], v[204:205], 0, s[2:3]
	global_load_dwordx4 v[80:83], v[206:207], off
	global_load_dwordx4 v[84:87], v[208:209], off
	s_min_u32 s2, s101, s100
	s_mul_i32 s2, s2, 0xf0000
	s_add_i32 s101, s101, 1
	v_lshl_add_u64 v[206:207], v[202:203], 0, s[2:3]
	v_lshl_add_u64 v[208:209], v[204:205], 0, s[2:3]
	global_load_dwordx4 v[88:91], v[206:207], off
	global_load_dwordx4 v[92:95], v[208:209], off

.LBB0_577:
	v_mov_b32_e32 v16, v191
	v_mov_b32_e32 v17, v191
	v_mov_b32_e32 v151, v191
	v_mov_b32_e32 v18, v191
	v_mov_b32_e32 v19, v191
	v_mov_b32_e32 v20, v191
	v_mov_b32_e32 v21, v191
	v_mov_b32_e32 v22, v191
	v_mov_b32_e32 v23, v191
	v_mov_b32_e32 v24, v191
	v_mov_b32_e32 v25, v191
	v_mov_b32_e32 v26, v191
	v_mov_b32_e32 v27, v191
	v_mov_b32_e32 v28, v191
	v_mov_b32_e32 v29, v191
	v_mov_b32_e32 v30, v191
	v_mov_b32_e32 v31, v191
	v_mov_b64_e32 v[124:125], v[140:141]
	v_mov_b64_e32 v[0:1], v[16:17]
	v_mov_b64_e32 v[116:117], v[136:137]
	v_mov_b64_e32 v[120:121], v[132:133]
	v_mov_b64_e32 v[112:113], v[128:129]
	s_mov_b64 s[36:37], 0
	v_mad_i64_i32 v[154:155], s[20:21], v152, s70, 0
	v_mov_b32_e32 v163, 0
	v_mov_b32_e32 v164, 0xf149f2ca
	v_mov_b64_e32 v[156:157], v[150:151]
	v_mov_b32_e32 v174, v173
	v_mov_b32_e32 v151, v172
	v_mov_b64_e32 v[126:127], v[142:143]
	v_mov_b64_e32 v[2:3], v[18:19]
	v_mov_b64_e32 v[4:5], v[20:21]
	v_mov_b64_e32 v[6:7], v[22:23]
	v_mov_b64_e32 v[8:9], v[24:25]
	v_mov_b64_e32 v[10:11], v[26:27]
	v_mov_b64_e32 v[12:13], v[28:29]
	v_mov_b64_e32 v[14:15], v[30:31]
	v_mov_b64_e32 v[118:119], v[138:139]
	v_mov_b64_e32 v[122:123], v[134:135]
	v_mov_b64_e32 v[114:115], v[130:131]
	v_and_b32_e32 v32, 16, v165
	v_lshlrev_b32_e32 v33, 2, v165
	v_and_or_b32 v32, v33, 12, v32
	v_lshl_or_b32 v32, v32, 1, v171
	v_mov_b32_e32 v181, v32
	v_lshlrev_b32_e32 v33, 4, v165
	v_and_b32_e32 v33, 0x70, v33
	v_or_b32_e32 v32, v154, v33
	v_mov_b32_e32 v33, v155
	s_nop 0
	v_lshl_add_u64 v[158:159], s[28:29], 0, v[32:33]
	v_or_b32_e32 v175, v170, v168
	v_or_b32_e32 v176, v166, v168
	v_or_b32_e32 v177, v167, v168
	v_or_b32_e32 v178, v169, v168
	v_lshlrev_b32_e32 v179, 2, v162
.LBB0_578:
	s_mov_b32 s35, s81
	v_lshl_add_u64 v[32:33], v[148:149], 0, s[34:35]
	v_lshlrev_b32_e32 v34, 1, v162
	v_mov_b32_e32 v35, v191
	v_lshl_add_u64 v[32:33], v[32:33], 0, v[34:35]
	s_mov_b64 s[20:21], 0x1a00
	v_lshl_add_u64 v[34:35], v[32:33], 0, s[20:21]
	v_add_co_u32_e32 v32, vcc, s76, v32
	s_lshl_b32 s35, s49, 1
	s_nop 0
	v_addc_co_u32_e32 v33, vcc, 0, v33, vcc
	global_load_dwordx2 v[132:133], v[34:35], off offset:16
	global_load_dwordx2 v[134:135], v[34:35], off offset:32
	global_load_dwordx2 v[136:137], v[34:35], off offset:48
	global_load_dwordx2 v[138:139], v[34:35], off offset:64
	global_load_dwordx2 v[130:131], v[32:33], off offset:2560
	global_load_dwordx2 v[140:141], v[34:35], off offset:80
	global_load_dwordx2 v[142:143], v[34:35], off offset:96
	global_load_dwordx2 v[128:129], v[34:35], off offset:112
	v_cmp_lt_i32_e32 vcc, v151, v174
	v_and_b32_e32 v34, 3, v165
	v_lshlrev_b32_e32 v34, 3, v34
	v_cndmask_b32_e32 v32, v227, v151, vcc
	v_lshlrev_b32_e32 v151, 2, v32
	v_and_b32_e32 v150, 31, v227
	v_lshrrev_b32_e32 v149, 5, v227
	v_lshlrev_b32_e32 v149, 2, v149
	v_sub_u32_e32 v150, v150, v149
	v_readfirstlane_b32 s51, v165
	s_nop 3
	s_lshr_b32 s51, s51, 6
	s_cmp_gt_u32 s51, 3
	s_cbranch_scc1 .Lfox_b0d4
	s_cmp_eq_u32 s51, 3
	s_cbranch_scc1 .Lfox_b0d3
	s_cmp_eq_u32 s51, 2
	s_cbranch_scc1 .Lfox_b0d2
	s_cmp_eq_u32 s51, 1
	s_cbranch_scc1 .Lfox_b0d1
.Lfox_b0d0:
	v_lshl_add_u64 v[112:113], v[158:159], 0, s[36:37]
	v_add_co_u32_e32 v116, vcc, 0x70f1000, v112
	s_nop 1
	v_addc_co_u32_e32 v117, vcc, 0, v113, vcc
	v_add_co_u32_e32 v182, vcc, 0x7169000, v112
	s_nop 1
	v_addc_co_u32_e32 v183, vcc, 0, v113, vcc
	global_load_dwordx4 v[112:115], v[116:117], off offset:512
	s_nop 0
	global_load_dwordx4 v[116:119], v[116:117], off offset:1536
	global_load_dwordx4 v[120:123], v[182:183], off offset:512
	global_load_dwordx4 v[124:127], v[182:183], off offset:1536
	ds_read_b128 v[32:35], v179
	ds_read_b128 v[36:39], v179 offset:32
	ds_read_b128 v[40:43], v179 offset:64
	ds_read_b128 v[44:47], v179 offset:96
	ds_read_b128 v[48:51], v175 offset:16384
	ds_read_b128 v[52:55], v176 offset:16384
	ds_read_b128 v[56:59], v177 offset:16384
	ds_read_b128 v[60:63], v178 offset:16384
	s_waitcnt lgkmcnt(3)
	v_mfma_f32_32x32x16_bf16 v[32:47], v[48:51], v[96:99], v[32:47]
	s_waitcnt lgkmcnt(2)
	v_mfma_f32_32x32x16_bf16 v[32:47], v[52:55], v[100:103], v[32:47]
	s_waitcnt lgkmcnt(1)
	v_mfma_f32_32x32x16_bf16 v[32:47], v[56:59], v[104:107], v[32:47]
	s_waitcnt lgkmcnt(0)
	v_mfma_f32_32x32x16_bf16 v[32:47], v[60:63], v[108:111], v[32:47]
	v_add_u32_e32 v218, 0xc000, v181
	ds_read_b64_tr_b16 v[202:203], v218 offset:0
	ds_read_b64_tr_b16 v[204:205], v218 offset:1536
	ds_read_b64_tr_b16 v[206:207], v218 offset:64
	ds_read_b64_tr_b16 v[208:209], v218 offset:1600
	ds_read_b64_tr_b16 v[210:211], v218 offset:3072
	ds_read_b64_tr_b16 v[212:213], v218 offset:4608
	ds_read_b64_tr_b16 v[214:215], v218 offset:3136
	ds_read_b64_tr_b16 v[216:217], v218 offset:4672
	v_cmp_gt_i32_e64 vcc, 0, v150
	v_cmp_gt_i32_e64 s[2:3], 1, v150
	v_cmp_gt_i32_e64 s[46:47], 2, v150
	v_cndmask_b32_e64 v32, v32, v228, vcc
	v_cmp_gt_i32_e64 vcc, 3, v150
	v_cndmask_b32_e64 v33, v33, v228, s[2:3]
	v_cmp_gt_i32_e64 s[2:3], 8, v150
	v_cndmask_b32_e64 v34, v34, v228, s[46:47]
	v_cmp_gt_i32_e64 s[46:47], 9, v150
	v_cndmask_b32_e64 v35, v35, v228, vcc
	v_cmp_gt_i32_e64 vcc, 10, v150
	v_cndmask_b32_e64 v36, v36, v228, s[2:3]
	v_cmp_gt_i32_e64 s[2:3], 11, v150
	v_cndmask_b32_e64 v37, v37, v228, s[46:47]
	v_cmp_gt_i32_e64 s[46:47], 16, v150
	v_cndmask_b32_e64 v38, v38, v228, vcc
	v_cmp_gt_i32_e64 vcc, 17, v150
	v_cndmask_b32_e64 v39, v39, v228, s[2:3]
	v_cmp_gt_i32_e64 s[2:3], 18, v150
	v_cndmask_b32_e64 v40, v40, v228, s[46:47]
	v_cmp_gt_i32_e64 s[46:47], 19, v150
	v_cndmask_b32_e64 v41, v41, v228, vcc
	v_cmp_gt_i32_e64 vcc, 24, v150
	v_cndmask_b32_e64 v42, v42, v228, s[2:3]
	v_cmp_gt_i32_e64 s[2:3], 25, v150
	v_cndmask_b32_e64 v43, v43, v228, s[46:47]
	v_cmp_gt_i32_e64 s[46:47], 26, v150
	v_cndmask_b32_e64 v44, v44, v228, vcc
	v_cmp_gt_i32_e64 vcc, 27, v150
	v_cndmask_b32_e64 v45, v45, v228, s[2:3]
	v_cndmask_b32_e64 v46, v46, v228, s[46:47]
	v_cndmask_b32_e64 v47, v47, v228, vcc
	v_max3_f32 v222, v32, v33, v34
	v_max3_f32 v222, v222, v35, v36
	v_max3_f32 v222, v222, v37, v38
	v_max3_f32 v222, v222, v39, v40
	v_max3_f32 v222, v222, v41, v42
	v_max3_f32 v222, v222, v43, v44
	v_max3_f32 v222, v222, v45, v46
	v_max_f32_e32 v222, v222, v47
	ds_bpermute_b32 v183, v151, v222
	s_waitcnt lgkmcnt(0)
	v_max_f32_e32 v183, v183, v183
	v_max_f32_e32 v182, v222, v183
	v_sub_f32_e32 v182, v182, v161
	v_add_f32_e32 v183, 0x40c00000, v164
	v_cmp_gt_f32_e32 vcc, v182, v183
	s_cbranch_vccz .Lfox_b0d0_pv
	v_max_f32_e32 v182, v182, v182
	v_max_f32_e32 v183, v164, v164
	v_max_f32_e32 v182, v183, v182
	v_sub_f32_e32 v164, v164, v182
	v_exp_f32_e32 v164, v164
	s_nop 0
	v_mul_f32_e32 v163, v163, v164
	v_pk_mul_f32 v[30:31], v[30:31], v[164:165] op_sel_hi:[1,0]
	v_pk_mul_f32 v[28:29], v[28:29], v[164:165] op_sel_hi:[1,0]
	v_pk_mul_f32 v[26:27], v[26:27], v[164:165] op_sel_hi:[1,0]
	v_pk_mul_f32 v[24:25], v[24:25], v[164:165] op_sel_hi:[1,0]
	v_pk_mul_f32 v[22:23], v[22:23], v[164:165] op_sel_hi:[1,0]
	v_pk_mul_f32 v[20:21], v[20:21], v[164:165] op_sel_hi:[1,0]
	v_pk_mul_f32 v[18:19], v[18:19], v[164:165] op_sel_hi:[1,0]
	v_pk_mul_f32 v[16:17], v[16:17], v[164:165] op_sel_hi:[1,0]
	v_pk_mul_f32 v[14:15], v[14:15], v[164:165] op_sel_hi:[1,0]
	v_pk_mul_f32 v[12:13], v[12:13], v[164:165] op_sel_hi:[1,0]
	v_pk_mul_f32 v[10:11], v[10:11], v[164:165] op_sel_hi:[1,0]
	v_pk_mul_f32 v[8:9], v[8:9], v[164:165] op_sel_hi:[1,0]
	v_pk_mul_f32 v[6:7], v[6:7], v[164:165] op_sel_hi:[1,0]
	v_pk_mul_f32 v[4:5], v[4:5], v[164:165] op_sel_hi:[1,0]
	v_pk_mul_f32 v[2:3], v[2:3], v[164:165] op_sel_hi:[1,0]
	v_pk_mul_f32 v[0:1], v[0:1], v[164:165] op_sel_hi:[1,0]
	v_mov_b32_e32 v164, v182
.Lfox_b0d0_pv:
	v_sub_f32_e64 v222, -v161, v164
	v_add_f32_e32 v32, v32, v222
	v_add_f32_e32 v33, v33, v222
	v_add_f32_e32 v34, v34, v222
	v_add_f32_e32 v35, v35, v222
	v_add_f32_e32 v36, v36, v222
	v_add_f32_e32 v37, v37, v222
	v_add_f32_e32 v38, v38, v222
	v_add_f32_e32 v39, v39, v222
	v_exp_f32_e32 v32, v32
	v_exp_f32_e32 v33, v33
	v_exp_f32_e32 v34, v34
	v_exp_f32_e32 v35, v35
	v_exp_f32_e32 v36, v36
	v_exp_f32_e32 v37, v37
	v_exp_f32_e32 v38, v38
	v_exp_f32_e32 v39, v39
	v_add_f32_e32 v182, v32, v33
	v_add_f32_e32 v183, v34, v35
	v_add_f32_e32 v182, v182, v36
	v_add_f32_e32 v183, v183, v37
	v_add_f32_e32 v182, v182, v38
	v_add_f32_e32 v183, v183, v39
	v_cvt_pk_bf16_f32 v32, v32, v33
	v_cvt_pk_bf16_f32 v33, v34, v35
	v_cvt_pk_bf16_f32 v34, v36, v37
	v_cvt_pk_bf16_f32 v35, v38, v39
	s_nop 1
	v_mfma_f32_32x32x16_bf16 v[16:31], v[202:205], v[32:35], v[16:31]
	v_add_f32_e32 v40, v40, v222
	v_add_f32_e32 v41, v41, v222
	v_add_f32_e32 v42, v42, v222
	v_add_f32_e32 v43, v43, v222
	v_add_f32_e32 v44, v44, v222
	v_add_f32_e32 v45, v45, v222
	v_add_f32_e32 v46, v46, v222
	v_add_f32_e32 v47, v47, v222
	v_exp_f32_e32 v40, v40
	v_exp_f32_e32 v41, v41
	v_exp_f32_e32 v42, v42
	v_exp_f32_e32 v43, v43
	v_exp_f32_e32 v44, v44
	v_exp_f32_e32 v45, v45
	v_exp_f32_e32 v46, v46
	v_exp_f32_e32 v47, v47
	v_mfma_f32_32x32x16_bf16 v[0:15], v[206:209], v[32:35], v[0:15]
	v_add_f32_e32 v182, v182, v40
	v_add_f32_e32 v183, v183, v41
	v_add_f32_e32 v182, v182, v42
	v_add_f32_e32 v183, v183, v43
	v_add_f32_e32 v182, v182, v44
	v_add_f32_e32 v183, v183, v45
	v_add_f32_e32 v182, v182, v46
	v_add_f32_e32 v183, v183, v47
	v_cvt_pk_bf16_f32 v40, v40, v41
	v_cvt_pk_bf16_f32 v41, v42, v43
	v_cvt_pk_bf16_f32 v42, v44, v45
	v_cvt_pk_bf16_f32 v43, v46, v47
	s_nop 1
	v_mfma_f32_32x32x16_bf16 v[16:31], v[210:213], v[40:43], v[16:31]
	v_mfma_f32_32x32x16_bf16 v[0:15], v[214:217], v[40:43], v[0:15]
	v_add_f32_e32 v163, v163, v182
	v_add_f32_e32 v163, v163, v183
	s_waitcnt vmcnt(3)
	ds_write_b128 v147, v[112:115] offset:32768
	s_waitcnt vmcnt(1)
	ds_write_b128 v147, v[120:123] offset:40960
	v_add_u32_e32 v222, 0x12000, v153
	ds_write_b128 v222, v[116:119]
	s_waitcnt vmcnt(0)
	ds_write_b128 v222, v[124:127] offset:12288
	s_waitcnt lgkmcnt(0)
	s_barrier
	s_branch .Lfox_band1
.Lfox_b0d1:
	v_lshl_add_u64 v[112:113], v[158:159], 0, s[36:37]
	v_add_co_u32_e32 v116, vcc, 0x70f1000, v112
	s_nop 1
	v_addc_co_u32_e32 v117, vcc, 0, v113, vcc
	v_add_co_u32_e32 v182, vcc, 0x7169000, v112
	s_nop 1
	v_addc_co_u32_e32 v183, vcc, 0, v113, vcc
	global_load_dwordx4 v[112:115], v[116:117], off offset:512
	s_nop 0
	global_load_dwordx4 v[116:119], v[116:117], off offset:1536
	global_load_dwordx4 v[120:123], v[182:183], off offset:512
	global_load_dwordx4 v[124:127], v[182:183], off offset:1536
	ds_read_b128 v[32:35], v179
	ds_read_b128 v[36:39], v179 offset:32
	ds_read_b128 v[40:43], v179 offset:64
	ds_read_b128 v[44:47], v179 offset:96
	ds_read_b128 v[48:51], v175 offset:16384
	ds_read_b128 v[52:55], v176 offset:16384
	ds_read_b128 v[56:59], v177 offset:16384
	ds_read_b128 v[60:63], v178 offset:16384
	ds_read_b128 v[80:83], v179 offset:128
	ds_read_b128 v[84:87], v179 offset:160
	ds_read_b128 v[88:91], v179 offset:192
	ds_read_b128 v[92:95], v179 offset:224
	s_waitcnt lgkmcnt(7)
	v_mfma_f32_32x32x16_bf16 v[32:47], v[48:51], v[96:99], v[32:47]
	ds_read_b128 v[64:67], v175 offset:20480
	s_waitcnt lgkmcnt(7)
	v_mfma_f32_32x32x16_bf16 v[32:47], v[52:55], v[100:103], v[32:47]
	ds_read_b128 v[68:71], v176 offset:20480
	s_waitcnt lgkmcnt(7)
	v_mfma_f32_32x32x16_bf16 v[32:47], v[56:59], v[104:107], v[32:47]
	ds_read_b128 v[72:75], v177 offset:20480
	s_waitcnt lgkmcnt(7)
	v_mfma_f32_32x32x16_bf16 v[32:47], v[60:63], v[108:111], v[32:47]
	ds_read_b128 v[76:79], v178 offset:20480
	s_waitcnt lgkmcnt(3)
	v_mfma_f32_32x32x16_bf16 v[80:95], v[64:67], v[96:99], v[80:95]
	s_waitcnt lgkmcnt(2)
	v_mfma_f32_32x32x16_bf16 v[80:95], v[68:71], v[100:103], v[80:95]
	s_waitcnt lgkmcnt(1)
	v_mfma_f32_32x32x16_bf16 v[80:95], v[72:75], v[104:107], v[80:95]
	s_waitcnt lgkmcnt(0)
	v_mfma_f32_32x32x16_bf16 v[80:95], v[76:79], v[108:111], v[80:95]
	v_add_u32_e32 v218, 0xc000, v181
	ds_read_b64_tr_b16 v[202:203], v218 offset:0
	ds_read_b64_tr_b16 v[204:205], v218 offset:1536
	ds_read_b64_tr_b16 v[206:207], v218 offset:64
	ds_read_b64_tr_b16 v[208:209], v218 offset:1600
	ds_read_b64_tr_b16 v[210:211], v218 offset:3072
	ds_read_b64_tr_b16 v[212:213], v218 offset:4608
	ds_read_b64_tr_b16 v[214:215], v218 offset:3136
	ds_read_b64_tr_b16 v[216:217], v218 offset:4672
	v_max3_f32 v222, v32, v33, v34
	v_max3_f32 v222, v222, v35, v36
	v_max3_f32 v222, v222, v37, v38
	v_max3_f32 v222, v222, v39, v40
	v_max3_f32 v222, v222, v41, v42
	v_max3_f32 v222, v222, v43, v44
	v_max3_f32 v222, v222, v45, v46
	v_cmp_gt_i32_e64 vcc, 0, v150
	v_cmp_gt_i32_e64 s[2:3], 1, v150
	v_cmp_gt_i32_e64 s[46:47], 2, v150
	v_cndmask_b32_e64 v80, v80, v228, vcc
	v_cmp_gt_i32_e64 vcc, 3, v150
	v_cndmask_b32_e64 v81, v81, v228, s[2:3]
	v_cmp_gt_i32_e64 s[2:3], 8, v150
	v_cndmask_b32_e64 v82, v82, v228, s[46:47]
	v_cmp_gt_i32_e64 s[46:47], 9, v150
	v_cndmask_b32_e64 v83, v83, v228, vcc
	v_cmp_gt_i32_e64 vcc, 10, v150
	v_cndmask_b32_e64 v84, v84, v228, s[2:3]
	v_cmp_gt_i32_e64 s[2:3], 11, v150
	v_cndmask_b32_e64 v85, v85, v228, s[46:47]
	v_cmp_gt_i32_e64 s[46:47], 16, v150
	v_cndmask_b32_e64 v86, v86, v228, vcc
	v_cmp_gt_i32_e64 vcc, 17, v150
	v_cndmask_b32_e64 v87, v87, v228, s[2:3]
	v_cmp_gt_i32_e64 s[2:3], 18, v150
	v_cndmask_b32_e64 v88, v88, v228, s[46:47]
	v_cmp_gt_i32_e64 s[46:47], 19, v150
	v_cndmask_b32_e64 v89, v89, v228, vcc
	v_cmp_gt_i32_e64 vcc, 24, v150
	v_cndmask_b32_e64 v90, v90, v228, s[2:3]
	v_cmp_gt_i32_e64 s[2:3], 25, v150
	v_cndmask_b32_e64 v91, v91, v228, s[46:47]
	v_cmp_gt_i32_e64 s[46:47], 26, v150
	v_cndmask_b32_e64 v92, v92, v228, vcc
	v_cmp_gt_i32_e64 vcc, 27, v150
	v_cndmask_b32_e64 v93, v93, v228, s[2:3]
	v_cndmask_b32_e64 v94, v94, v228, s[46:47]
	v_cndmask_b32_e64 v95, v95, v228, vcc
	v_max3_f32 v222, v222, v47, v80
	v_max3_f32 v222, v222, v81, v82
	v_max3_f32 v222, v222, v83, v84
	v_max3_f32 v222, v222, v85, v86
	v_max3_f32 v222, v222, v87, v88
	v_max3_f32 v222, v222, v89, v90
	v_max3_f32 v222, v222, v91, v92
	v_max3_f32 v222, v222, v93, v94
	v_max_f32_e32 v222, v222, v95
	ds_bpermute_b32 v183, v151, v222
	s_waitcnt lgkmcnt(0)
	v_max_f32_e32 v183, v183, v183
	v_max_f32_e32 v182, v222, v183
	v_sub_f32_e32 v182, v182, v161
	v_add_f32_e32 v183, 0x40c00000, v164
	v_cmp_gt_f32_e32 vcc, v182, v183
	s_cbranch_vccz .Lfox_b0d1_pv
	v_max_f32_e32 v182, v182, v182
	v_max_f32_e32 v183, v164, v164
	v_max_f32_e32 v182, v183, v182
	v_sub_f32_e32 v164, v164, v182
	v_exp_f32_e32 v164, v164
	s_nop 0
	v_mul_f32_e32 v163, v163, v164
	v_pk_mul_f32 v[30:31], v[30:31], v[164:165] op_sel_hi:[1,0]
	v_pk_mul_f32 v[28:29], v[28:29], v[164:165] op_sel_hi:[1,0]
	v_pk_mul_f32 v[26:27], v[26:27], v[164:165] op_sel_hi:[1,0]
	v_pk_mul_f32 v[24:25], v[24:25], v[164:165] op_sel_hi:[1,0]
	v_pk_mul_f32 v[22:23], v[22:23], v[164:165] op_sel_hi:[1,0]
	v_pk_mul_f32 v[20:21], v[20:21], v[164:165] op_sel_hi:[1,0]
	v_pk_mul_f32 v[18:19], v[18:19], v[164:165] op_sel_hi:[1,0]
	v_pk_mul_f32 v[16:17], v[16:17], v[164:165] op_sel_hi:[1,0]
	v_pk_mul_f32 v[14:15], v[14:15], v[164:165] op_sel_hi:[1,0]
	v_pk_mul_f32 v[12:13], v[12:13], v[164:165] op_sel_hi:[1,0]
	v_pk_mul_f32 v[10:11], v[10:11], v[164:165] op_sel_hi:[1,0]
	v_pk_mul_f32 v[8:9], v[8:9], v[164:165] op_sel_hi:[1,0]
	v_pk_mul_f32 v[6:7], v[6:7], v[164:165] op_sel_hi:[1,0]
	v_pk_mul_f32 v[4:5], v[4:5], v[164:165] op_sel_hi:[1,0]
	v_pk_mul_f32 v[2:3], v[2:3], v[164:165] op_sel_hi:[1,0]
	v_pk_mul_f32 v[0:1], v[0:1], v[164:165] op_sel_hi:[1,0]
	v_mov_b32_e32 v164, v182
.Lfox_b0d1_pv:
	v_sub_f32_e64 v222, -v161, v164
	v_add_f32_e32 v32, v32, v222
	v_add_f32_e32 v33, v33, v222
	v_add_f32_e32 v34, v34, v222
	v_add_f32_e32 v35, v35, v222
	v_add_f32_e32 v36, v36, v222
	v_add_f32_e32 v37, v37, v222
	v_add_f32_e32 v38, v38, v222
	v_add_f32_e32 v39, v39, v222
	v_exp_f32_e32 v32, v32
	v_exp_f32_e32 v33, v33
	v_exp_f32_e32 v34, v34
	v_exp_f32_e32 v35, v35
	v_exp_f32_e32 v36, v36
	v_exp_f32_e32 v37, v37
	v_exp_f32_e32 v38, v38
	v_exp_f32_e32 v39, v39
	v_add_f32_e32 v182, v32, v33
	v_add_f32_e32 v183, v34, v35
	v_add_f32_e32 v182, v182, v36
	v_add_f32_e32 v183, v183, v37
	v_add_f32_e32 v182, v182, v38
	v_add_f32_e32 v183, v183, v39
	v_cvt_pk_bf16_f32 v32, v32, v33
	v_cvt_pk_bf16_f32 v33, v34, v35
	v_cvt_pk_bf16_f32 v34, v36, v37
	v_cvt_pk_bf16_f32 v35, v38, v39
	s_nop 1
	v_mfma_f32_32x32x16_bf16 v[16:31], v[202:205], v[32:35], v[16:31]
	v_add_f32_e32 v40, v40, v222
	v_add_f32_e32 v41, v41, v222
	v_add_f32_e32 v42, v42, v222
	v_add_f32_e32 v43, v43, v222
	v_add_f32_e32 v44, v44, v222
	v_add_f32_e32 v45, v45, v222
	v_add_f32_e32 v46, v46, v222
	v_add_f32_e32 v47, v47, v222
	v_exp_f32_e32 v40, v40
	v_exp_f32_e32 v41, v41
	v_exp_f32_e32 v42, v42
	v_exp_f32_e32 v43, v43
	v_exp_f32_e32 v44, v44
	v_exp_f32_e32 v45, v45
	v_exp_f32_e32 v46, v46
	v_exp_f32_e32 v47, v47
	v_mfma_f32_32x32x16_bf16 v[0:15], v[206:209], v[32:35], v[0:15]
	ds_read_b64_tr_b16 v[202:203], v218 offset:6144
	ds_read_b64_tr_b16 v[204:205], v218 offset:7680
	ds_read_b64_tr_b16 v[206:207], v218 offset:6208
	ds_read_b64_tr_b16 v[208:209], v218 offset:7744
	v_add_f32_e32 v182, v182, v40
	v_add_f32_e32 v183, v183, v41
	v_add_f32_e32 v182, v182, v42
	v_add_f32_e32 v183, v183, v43
	v_add_f32_e32 v182, v182, v44
	v_add_f32_e32 v183, v183, v45
	v_add_f32_e32 v182, v182, v46
	v_add_f32_e32 v183, v183, v47
	v_cvt_pk_bf16_f32 v40, v40, v41
	v_cvt_pk_bf16_f32 v41, v42, v43
	v_cvt_pk_bf16_f32 v42, v44, v45
	v_cvt_pk_bf16_f32 v43, v46, v47
	s_nop 1
	v_mfma_f32_32x32x16_bf16 v[16:31], v[210:213], v[40:43], v[16:31]
	v_add_f32_e32 v80, v80, v222
	v_add_f32_e32 v81, v81, v222
	v_add_f32_e32 v82, v82, v222
	v_add_f32_e32 v83, v83, v222
	v_add_f32_e32 v84, v84, v222
	v_add_f32_e32 v85, v85, v222
	v_add_f32_e32 v86, v86, v222
	v_add_f32_e32 v87, v87, v222
	v_exp_f32_e32 v80, v80
	v_exp_f32_e32 v81, v81
	v_exp_f32_e32 v82, v82
	v_exp_f32_e32 v83, v83
	v_exp_f32_e32 v84, v84
	v_exp_f32_e32 v85, v85
	v_exp_f32_e32 v86, v86
	v_exp_f32_e32 v87, v87
	v_mfma_f32_32x32x16_bf16 v[0:15], v[214:217], v[40:43], v[0:15]
	ds_read_b64_tr_b16 v[210:211], v218 offset:9216
	ds_read_b64_tr_b16 v[212:213], v218 offset:10752
	ds_read_b64_tr_b16 v[214:215], v218 offset:9280
	ds_read_b64_tr_b16 v[216:217], v218 offset:10816
	v_add_f32_e32 v182, v182, v80
	v_add_f32_e32 v183, v183, v81
	v_add_f32_e32 v182, v182, v82
	v_add_f32_e32 v183, v183, v83
	v_add_f32_e32 v182, v182, v84
	v_add_f32_e32 v183, v183, v85
	v_add_f32_e32 v182, v182, v86
	v_add_f32_e32 v183, v183, v87
	v_cvt_pk_bf16_f32 v80, v80, v81
	v_cvt_pk_bf16_f32 v81, v82, v83
	v_cvt_pk_bf16_f32 v82, v84, v85
	v_cvt_pk_bf16_f32 v83, v86, v87
	s_waitcnt lgkmcnt(6)
	s_nop 0
	v_mfma_f32_32x32x16_bf16 v[16:31], v[202:205], v[80:83], v[16:31]
	v_add_f32_e32 v88, v88, v222
	v_add_f32_e32 v89, v89, v222
	v_add_f32_e32 v90, v90, v222
	v_add_f32_e32 v91, v91, v222
	v_add_f32_e32 v92, v92, v222
	v_add_f32_e32 v93, v93, v222
	v_add_f32_e32 v94, v94, v222
	v_add_f32_e32 v95, v95, v222
	v_exp_f32_e32 v88, v88
	v_exp_f32_e32 v89, v89
	v_exp_f32_e32 v90, v90
	v_exp_f32_e32 v91, v91
	v_exp_f32_e32 v92, v92
	v_exp_f32_e32 v93, v93
	v_exp_f32_e32 v94, v94
	v_exp_f32_e32 v95, v95
	s_waitcnt lgkmcnt(4)
	v_mfma_f32_32x32x16_bf16 v[0:15], v[206:209], v[80:83], v[0:15]
	v_add_f32_e32 v182, v182, v88
	v_add_f32_e32 v183, v183, v89
	v_add_f32_e32 v182, v182, v90
	v_add_f32_e32 v183, v183, v91
	v_add_f32_e32 v182, v182, v92
	v_add_f32_e32 v183, v183, v93
	v_add_f32_e32 v182, v182, v94
	v_add_f32_e32 v183, v183, v95
	v_cvt_pk_bf16_f32 v88, v88, v89
	v_cvt_pk_bf16_f32 v89, v90, v91
	v_cvt_pk_bf16_f32 v90, v92, v93
	v_cvt_pk_bf16_f32 v91, v94, v95
	s_waitcnt lgkmcnt(2)
	s_nop 0
	v_mfma_f32_32x32x16_bf16 v[16:31], v[210:213], v[88:91], v[16:31]
	s_waitcnt lgkmcnt(0)
	v_mfma_f32_32x32x16_bf16 v[0:15], v[214:217], v[88:91], v[0:15]
	v_add_f32_e32 v163, v163, v182
	v_add_f32_e32 v163, v163, v183
	s_waitcnt vmcnt(3)
	ds_write_b128 v147, v[112:115] offset:32768
	s_waitcnt vmcnt(1)
	ds_write_b128 v147, v[120:123] offset:40960
	v_add_u32_e32 v222, 0x12000, v153
	ds_write_b128 v222, v[116:119]
	s_waitcnt vmcnt(0)
	ds_write_b128 v222, v[124:127] offset:12288
	s_waitcnt lgkmcnt(0)
	s_barrier
	s_branch .Lfox_band1
.Lfox_b0d2:
	v_lshl_add_u64 v[112:113], v[158:159], 0, s[36:37]
	v_add_co_u32_e32 v116, vcc, 0x70f1000, v112
	s_nop 1
	v_addc_co_u32_e32 v117, vcc, 0, v113, vcc
	v_add_co_u32_e32 v182, vcc, 0x7169000, v112
	s_nop 1
	v_addc_co_u32_e32 v183, vcc, 0, v113, vcc
	global_load_dwordx4 v[112:115], v[116:117], off offset:512
	s_nop 0
	global_load_dwordx4 v[116:119], v[116:117], off offset:1536
	global_load_dwordx4 v[120:123], v[182:183], off offset:512
	global_load_dwordx4 v[124:127], v[182:183], off offset:1536
	ds_read_b128 v[32:35], v179
	ds_read_b128 v[36:39], v179 offset:32
	ds_read_b128 v[40:43], v179 offset:64
	ds_read_b128 v[44:47], v179 offset:96
	ds_read_b128 v[48:51], v175 offset:16384
	ds_read_b128 v[52:55], v176 offset:16384
	ds_read_b128 v[56:59], v177 offset:16384
	ds_read_b128 v[60:63], v178 offset:16384
	ds_read_b128 v[80:83], v179 offset:128
	ds_read_b128 v[84:87], v179 offset:160
	ds_read_b128 v[88:91], v179 offset:192
	ds_read_b128 v[92:95], v179 offset:224
	s_waitcnt lgkmcnt(7)
	v_mfma_f32_32x32x16_bf16 v[32:47], v[48:51], v[96:99], v[32:47]
	ds_read_b128 v[64:67], v175 offset:20480
	s_waitcnt lgkmcnt(7)
	v_mfma_f32_32x32x16_bf16 v[32:47], v[52:55], v[100:103], v[32:47]
	ds_read_b128 v[68:71], v176 offset:20480
	s_waitcnt lgkmcnt(7)
	v_mfma_f32_32x32x16_bf16 v[32:47], v[56:59], v[104:107], v[32:47]
	ds_read_b128 v[72:75], v177 offset:20480
	s_waitcnt lgkmcnt(7)
	v_mfma_f32_32x32x16_bf16 v[32:47], v[60:63], v[108:111], v[32:47]
	ds_read_b128 v[76:79], v178 offset:20480
	ds_read_b128 v[48:51], v179 offset:256
	ds_read_b128 v[52:55], v179 offset:288
	ds_read_b128 v[56:59], v179 offset:320
	ds_read_b128 v[60:63], v179 offset:352
	s_waitcnt lgkmcnt(7)
	v_mfma_f32_32x32x16_bf16 v[80:95], v[64:67], v[96:99], v[80:95]
	ds_read_b128 v[202:205], v175 offset:24576
	s_waitcnt lgkmcnt(7)
	v_mfma_f32_32x32x16_bf16 v[80:95], v[68:71], v[100:103], v[80:95]
	ds_read_b128 v[206:209], v176 offset:24576
	s_waitcnt lgkmcnt(7)
	v_mfma_f32_32x32x16_bf16 v[80:95], v[72:75], v[104:107], v[80:95]
	ds_read_b128 v[210:213], v177 offset:24576
	s_waitcnt lgkmcnt(7)
	v_mfma_f32_32x32x16_bf16 v[80:95], v[76:79], v[108:111], v[80:95]
	ds_read_b128 v[214:217], v178 offset:24576
	v_max3_f32 v222, v32, v33, v34
	v_max3_f32 v222, v222, v35, v36
	v_max3_f32 v222, v222, v37, v38
	v_max3_f32 v222, v222, v39, v40
	v_max3_f32 v222, v222, v41, v42
	v_max3_f32 v222, v222, v43, v44
	v_max3_f32 v222, v222, v45, v46
	s_waitcnt lgkmcnt(3)
	v_mfma_f32_32x32x16_bf16 v[48:63], v[202:205], v[96:99], v[48:63]
	s_waitcnt lgkmcnt(2)
	v_mfma_f32_32x32x16_bf16 v[48:63], v[206:209], v[100:103], v[48:63]
	s_waitcnt lgkmcnt(1)
	v_mfma_f32_32x32x16_bf16 v[48:63], v[210:213], v[104:107], v[48:63]
	s_waitcnt lgkmcnt(0)
	v_mfma_f32_32x32x16_bf16 v[48:63], v[214:217], v[108:111], v[48:63]
	v_max3_f32 v222, v222, v47, v80
	v_max3_f32 v222, v222, v81, v82
	v_max3_f32 v222, v222, v83, v84
	v_max3_f32 v222, v222, v85, v86
	v_max3_f32 v222, v222, v87, v88
	v_max3_f32 v222, v222, v89, v90
	v_max3_f32 v222, v222, v91, v92
	v_max3_f32 v222, v222, v93, v94
	v_add_u32_e32 v218, 0xc000, v181
	ds_read_b64_tr_b16 v[202:203], v218 offset:0
	ds_read_b64_tr_b16 v[204:205], v218 offset:1536
	ds_read_b64_tr_b16 v[206:207], v218 offset:64
	ds_read_b64_tr_b16 v[208:209], v218 offset:1600
	ds_read_b64_tr_b16 v[210:211], v218 offset:3072
	ds_read_b64_tr_b16 v[212:213], v218 offset:4608
	ds_read_b64_tr_b16 v[214:215], v218 offset:3136
	ds_read_b64_tr_b16 v[216:217], v218 offset:4672
	v_cmp_gt_i32_e64 vcc, 0, v150
	v_cmp_gt_i32_e64 s[2:3], 1, v150
	v_cmp_gt_i32_e64 s[46:47], 2, v150
	v_cndmask_b32_e64 v48, v48, v228, vcc
	v_cmp_gt_i32_e64 vcc, 3, v150
	v_cndmask_b32_e64 v49, v49, v228, s[2:3]
	v_cmp_gt_i32_e64 s[2:3], 8, v150
	v_cndmask_b32_e64 v50, v50, v228, s[46:47]
	v_cmp_gt_i32_e64 s[46:47], 9, v150
	v_cndmask_b32_e64 v51, v51, v228, vcc
	v_cmp_gt_i32_e64 vcc, 10, v150
	v_cndmask_b32_e64 v52, v52, v228, s[2:3]
	v_cmp_gt_i32_e64 s[2:3], 11, v150
	v_cndmask_b32_e64 v53, v53, v228, s[46:47]
	v_cmp_gt_i32_e64 s[46:47], 16, v150
	v_cndmask_b32_e64 v54, v54, v228, vcc
	v_cmp_gt_i32_e64 vcc, 17, v150
	v_cndmask_b32_e64 v55, v55, v228, s[2:3]
	v_cmp_gt_i32_e64 s[2:3], 18, v150
	v_cndmask_b32_e64 v56, v56, v228, s[46:47]
	v_cmp_gt_i32_e64 s[46:47], 19, v150
	v_cndmask_b32_e64 v57, v57, v228, vcc
	v_cmp_gt_i32_e64 vcc, 24, v150
	v_cndmask_b32_e64 v58, v58, v228, s[2:3]
	v_cmp_gt_i32_e64 s[2:3], 25, v150
	v_cndmask_b32_e64 v59, v59, v228, s[46:47]
	v_cmp_gt_i32_e64 s[46:47], 26, v150
	v_cndmask_b32_e64 v60, v60, v228, vcc
	v_cmp_gt_i32_e64 vcc, 27, v150
	v_cndmask_b32_e64 v61, v61, v228, s[2:3]
	v_cndmask_b32_e64 v62, v62, v228, s[46:47]
	v_cndmask_b32_e64 v63, v63, v228, vcc
	v_max3_f32 v222, v222, v95, v48
	v_max3_f32 v222, v222, v49, v50
	v_max3_f32 v222, v222, v51, v52
	v_max3_f32 v222, v222, v53, v54
	v_max3_f32 v222, v222, v55, v56
	v_max3_f32 v222, v222, v57, v58
	v_max3_f32 v222, v222, v59, v60
	v_max3_f32 v222, v222, v61, v62
	v_max_f32_e32 v222, v222, v63
	ds_bpermute_b32 v183, v151, v222
	s_waitcnt lgkmcnt(0)
	v_max_f32_e32 v183, v183, v183
	v_max_f32_e32 v182, v222, v183
	v_sub_f32_e32 v182, v182, v161
	v_add_f32_e32 v183, 0x40c00000, v164
	v_cmp_gt_f32_e32 vcc, v182, v183
	s_cbranch_vccz .Lfox_b0d2_pv
	v_max_f32_e32 v182, v182, v182
	v_max_f32_e32 v183, v164, v164
	v_max_f32_e32 v182, v183, v182
	v_sub_f32_e32 v164, v164, v182
	v_exp_f32_e32 v164, v164
	s_nop 0
	v_mul_f32_e32 v163, v163, v164
	v_pk_mul_f32 v[30:31], v[30:31], v[164:165] op_sel_hi:[1,0]
	v_pk_mul_f32 v[28:29], v[28:29], v[164:165] op_sel_hi:[1,0]
	v_pk_mul_f32 v[26:27], v[26:27], v[164:165] op_sel_hi:[1,0]
	v_pk_mul_f32 v[24:25], v[24:25], v[164:165] op_sel_hi:[1,0]
	v_pk_mul_f32 v[22:23], v[22:23], v[164:165] op_sel_hi:[1,0]
	v_pk_mul_f32 v[20:21], v[20:21], v[164:165] op_sel_hi:[1,0]
	v_pk_mul_f32 v[18:19], v[18:19], v[164:165] op_sel_hi:[1,0]
	v_pk_mul_f32 v[16:17], v[16:17], v[164:165] op_sel_hi:[1,0]
	v_pk_mul_f32 v[14:15], v[14:15], v[164:165] op_sel_hi:[1,0]
	v_pk_mul_f32 v[12:13], v[12:13], v[164:165] op_sel_hi:[1,0]
	v_pk_mul_f32 v[10:11], v[10:11], v[164:165] op_sel_hi:[1,0]
	v_pk_mul_f32 v[8:9], v[8:9], v[164:165] op_sel_hi:[1,0]
	v_pk_mul_f32 v[6:7], v[6:7], v[164:165] op_sel_hi:[1,0]
	v_pk_mul_f32 v[4:5], v[4:5], v[164:165] op_sel_hi:[1,0]
	v_pk_mul_f32 v[2:3], v[2:3], v[164:165] op_sel_hi:[1,0]
	v_pk_mul_f32 v[0:1], v[0:1], v[164:165] op_sel_hi:[1,0]
	v_mov_b32_e32 v164, v182
.Lfox_b0d2_pv:
	v_sub_f32_e64 v222, -v161, v164
	v_add_f32_e32 v32, v32, v222
	v_add_f32_e32 v33, v33, v222
	v_add_f32_e32 v34, v34, v222
	v_add_f32_e32 v35, v35, v222
	v_add_f32_e32 v36, v36, v222
	v_add_f32_e32 v37, v37, v222
	v_add_f32_e32 v38, v38, v222
	v_add_f32_e32 v39, v39, v222
	v_exp_f32_e32 v32, v32
	v_exp_f32_e32 v33, v33
	v_exp_f32_e32 v34, v34
	v_exp_f32_e32 v35, v35
	v_exp_f32_e32 v36, v36
	v_exp_f32_e32 v37, v37
	v_exp_f32_e32 v38, v38
	v_exp_f32_e32 v39, v39
	v_add_f32_e32 v182, v32, v33
	v_add_f32_e32 v183, v34, v35
	v_add_f32_e32 v182, v182, v36
	v_add_f32_e32 v183, v183, v37
	v_add_f32_e32 v182, v182, v38
	v_add_f32_e32 v183, v183, v39
	v_cvt_pk_bf16_f32 v32, v32, v33
	v_cvt_pk_bf16_f32 v33, v34, v35
	v_cvt_pk_bf16_f32 v34, v36, v37
	v_cvt_pk_bf16_f32 v35, v38, v39
	s_nop 1
	v_mfma_f32_32x32x16_bf16 v[16:31], v[202:205], v[32:35], v[16:31]
	v_add_f32_e32 v40, v40, v222
	v_add_f32_e32 v41, v41, v222
	v_add_f32_e32 v42, v42, v222
	v_add_f32_e32 v43, v43, v222
	v_add_f32_e32 v44, v44, v222
	v_add_f32_e32 v45, v45, v222
	v_add_f32_e32 v46, v46, v222
	v_add_f32_e32 v47, v47, v222
	v_exp_f32_e32 v40, v40
	v_exp_f32_e32 v41, v41
	v_exp_f32_e32 v42, v42
	v_exp_f32_e32 v43, v43
	v_exp_f32_e32 v44, v44
	v_exp_f32_e32 v45, v45
	v_exp_f32_e32 v46, v46
	v_exp_f32_e32 v47, v47
	v_mfma_f32_32x32x16_bf16 v[0:15], v[206:209], v[32:35], v[0:15]
	ds_read_b64_tr_b16 v[202:203], v218 offset:6144
	ds_read_b64_tr_b16 v[204:205], v218 offset:7680
	ds_read_b64_tr_b16 v[206:207], v218 offset:6208
	ds_read_b64_tr_b16 v[208:209], v218 offset:7744
	v_add_f32_e32 v182, v182, v40
	v_add_f32_e32 v183, v183, v41
	v_add_f32_e32 v182, v182, v42
	v_add_f32_e32 v183, v183, v43
	v_add_f32_e32 v182, v182, v44
	v_add_f32_e32 v183, v183, v45
	v_add_f32_e32 v182, v182, v46
	v_add_f32_e32 v183, v183, v47
	v_cvt_pk_bf16_f32 v40, v40, v41
	v_cvt_pk_bf16_f32 v41, v42, v43
	v_cvt_pk_bf16_f32 v42, v44, v45
	v_cvt_pk_bf16_f32 v43, v46, v47
	s_nop 1
	v_mfma_f32_32x32x16_bf16 v[16:31], v[210:213], v[40:43], v[16:31]
	v_add_f32_e32 v80, v80, v222
	v_add_f32_e32 v81, v81, v222
	v_add_f32_e32 v82, v82, v222
	v_add_f32_e32 v83, v83, v222
	v_add_f32_e32 v84, v84, v222
	v_add_f32_e32 v85, v85, v222
	v_add_f32_e32 v86, v86, v222
	v_add_f32_e32 v87, v87, v222
	v_exp_f32_e32 v80, v80
	v_exp_f32_e32 v81, v81
	v_exp_f32_e32 v82, v82
	v_exp_f32_e32 v83, v83
	v_exp_f32_e32 v84, v84
	v_exp_f32_e32 v85, v85
	v_exp_f32_e32 v86, v86
	v_exp_f32_e32 v87, v87
	v_mfma_f32_32x32x16_bf16 v[0:15], v[214:217], v[40:43], v[0:15]
	ds_read_b64_tr_b16 v[210:211], v218 offset:9216
	ds_read_b64_tr_b16 v[212:213], v218 offset:10752
	ds_read_b64_tr_b16 v[214:215], v218 offset:9280
	ds_read_b64_tr_b16 v[216:217], v218 offset:10816
	v_add_f32_e32 v182, v182, v80
	v_add_f32_e32 v183, v183, v81
	v_add_f32_e32 v182, v182, v82
	v_add_f32_e32 v183, v183, v83
	v_add_f32_e32 v182, v182, v84
	v_add_f32_e32 v183, v183, v85
	v_add_f32_e32 v182, v182, v86
	v_add_f32_e32 v183, v183, v87
	v_cvt_pk_bf16_f32 v80, v80, v81
	v_cvt_pk_bf16_f32 v81, v82, v83
	v_cvt_pk_bf16_f32 v82, v84, v85
	v_cvt_pk_bf16_f32 v83, v86, v87
	s_waitcnt lgkmcnt(6)
	s_nop 0
	v_mfma_f32_32x32x16_bf16 v[16:31], v[202:205], v[80:83], v[16:31]
	v_add_f32_e32 v88, v88, v222
	v_add_f32_e32 v89, v89, v222
	v_add_f32_e32 v90, v90, v222
	v_add_f32_e32 v91, v91, v222
	v_add_f32_e32 v92, v92, v222
	v_add_f32_e32 v93, v93, v222
	v_add_f32_e32 v94, v94, v222
	v_add_f32_e32 v95, v95, v222
	v_exp_f32_e32 v88, v88
	v_exp_f32_e32 v89, v89
	v_exp_f32_e32 v90, v90
	v_exp_f32_e32 v91, v91
	v_exp_f32_e32 v92, v92
	v_exp_f32_e32 v93, v93
	v_exp_f32_e32 v94, v94
	v_exp_f32_e32 v95, v95
	s_waitcnt lgkmcnt(4)
	v_mfma_f32_32x32x16_bf16 v[0:15], v[206:209], v[80:83], v[0:15]
	ds_read_b64_tr_b16 v[202:203], v218 offset:12288
	ds_read_b64_tr_b16 v[204:205], v218 offset:13824
	ds_read_b64_tr_b16 v[206:207], v218 offset:12352
	ds_read_b64_tr_b16 v[208:209], v218 offset:13888
	v_add_f32_e32 v182, v182, v88
	v_add_f32_e32 v183, v183, v89
	v_add_f32_e32 v182, v182, v90
	v_add_f32_e32 v183, v183, v91
	v_add_f32_e32 v182, v182, v92
	v_add_f32_e32 v183, v183, v93
	v_add_f32_e32 v182, v182, v94
	v_add_f32_e32 v183, v183, v95
	v_cvt_pk_bf16_f32 v88, v88, v89
	v_cvt_pk_bf16_f32 v89, v90, v91
	v_cvt_pk_bf16_f32 v90, v92, v93
	v_cvt_pk_bf16_f32 v91, v94, v95
	s_waitcnt lgkmcnt(6)
	s_nop 0
	v_mfma_f32_32x32x16_bf16 v[16:31], v[210:213], v[88:91], v[16:31]
	v_add_f32_e32 v48, v48, v222
	v_add_f32_e32 v49, v49, v222
	v_add_f32_e32 v50, v50, v222
	v_add_f32_e32 v51, v51, v222
	v_add_f32_e32 v52, v52, v222
	v_add_f32_e32 v53, v53, v222
	v_add_f32_e32 v54, v54, v222
	v_add_f32_e32 v55, v55, v222
	v_exp_f32_e32 v48, v48
	v_exp_f32_e32 v49, v49
	v_exp_f32_e32 v50, v50
	v_exp_f32_e32 v51, v51
	v_exp_f32_e32 v52, v52
	v_exp_f32_e32 v53, v53
	v_exp_f32_e32 v54, v54
	v_exp_f32_e32 v55, v55
	s_waitcnt lgkmcnt(4)
	v_mfma_f32_32x32x16_bf16 v[0:15], v[214:217], v[88:91], v[0:15]
	ds_read_b64_tr_b16 v[210:211], v218 offset:15360
	ds_read_b64_tr_b16 v[212:213], v218 offset:16896
	ds_read_b64_tr_b16 v[214:215], v218 offset:15424
	ds_read_b64_tr_b16 v[216:217], v218 offset:16960
	v_add_f32_e32 v182, v182, v48
	v_add_f32_e32 v183, v183, v49
	v_add_f32_e32 v182, v182, v50
	v_add_f32_e32 v183, v183, v51
	v_add_f32_e32 v182, v182, v52
	v_add_f32_e32 v183, v183, v53
	v_add_f32_e32 v182, v182, v54
	v_add_f32_e32 v183, v183, v55
	v_cvt_pk_bf16_f32 v48, v48, v49
	v_cvt_pk_bf16_f32 v49, v50, v51
	v_cvt_pk_bf16_f32 v50, v52, v53
	v_cvt_pk_bf16_f32 v51, v54, v55
	s_waitcnt lgkmcnt(6)
	s_nop 0
	v_mfma_f32_32x32x16_bf16 v[16:31], v[202:205], v[48:51], v[16:31]
	v_add_f32_e32 v56, v56, v222
	v_add_f32_e32 v57, v57, v222
	v_add_f32_e32 v58, v58, v222
	v_add_f32_e32 v59, v59, v222
	v_add_f32_e32 v60, v60, v222
	v_add_f32_e32 v61, v61, v222
	v_add_f32_e32 v62, v62, v222
	v_add_f32_e32 v63, v63, v222
	v_exp_f32_e32 v56, v56
	v_exp_f32_e32 v57, v57
	v_exp_f32_e32 v58, v58
	v_exp_f32_e32 v59, v59
	v_exp_f32_e32 v60, v60
	v_exp_f32_e32 v61, v61
	v_exp_f32_e32 v62, v62
	v_exp_f32_e32 v63, v63
	s_waitcnt lgkmcnt(4)
	v_mfma_f32_32x32x16_bf16 v[0:15], v[206:209], v[48:51], v[0:15]
	v_add_f32_e32 v182, v182, v56
	v_add_f32_e32 v183, v183, v57
	v_add_f32_e32 v182, v182, v58
	v_add_f32_e32 v183, v183, v59
	v_add_f32_e32 v182, v182, v60
	v_add_f32_e32 v183, v183, v61
	v_add_f32_e32 v182, v182, v62
	v_add_f32_e32 v183, v183, v63
	v_cvt_pk_bf16_f32 v56, v56, v57
	v_cvt_pk_bf16_f32 v57, v58, v59
	v_cvt_pk_bf16_f32 v58, v60, v61
	v_cvt_pk_bf16_f32 v59, v62, v63
	s_waitcnt lgkmcnt(2)
	s_nop 0
	v_mfma_f32_32x32x16_bf16 v[16:31], v[210:213], v[56:59], v[16:31]
	s_waitcnt lgkmcnt(0)
	v_mfma_f32_32x32x16_bf16 v[0:15], v[214:217], v[56:59], v[0:15]
	v_add_f32_e32 v163, v163, v182
	v_add_f32_e32 v163, v163, v183
	s_waitcnt vmcnt(3)
	ds_write_b128 v147, v[112:115] offset:32768
	s_waitcnt vmcnt(1)
	ds_write_b128 v147, v[120:123] offset:40960
	v_add_u32_e32 v222, 0x12000, v153
	ds_write_b128 v222, v[116:119]
	s_waitcnt vmcnt(0)
	ds_write_b128 v222, v[124:127] offset:12288
	s_waitcnt lgkmcnt(0)
	s_barrier
	s_branch .Lfox_band1
.Lfox_b0d3:
	v_lshl_add_u64 v[112:113], v[158:159], 0, s[36:37]
	v_add_co_u32_e32 v116, vcc, 0x70f1000, v112
	s_nop 1
	v_addc_co_u32_e32 v117, vcc, 0, v113, vcc
	v_add_co_u32_e32 v182, vcc, 0x7169000, v112
	s_nop 1
	v_addc_co_u32_e32 v183, vcc, 0, v113, vcc
	global_load_dwordx4 v[112:115], v[116:117], off offset:512
	s_nop 0
	global_load_dwordx4 v[116:119], v[116:117], off offset:1536
	global_load_dwordx4 v[120:123], v[182:183], off offset:512
	global_load_dwordx4 v[124:127], v[182:183], off offset:1536
	ds_read_b128 v[32:35], v179
	ds_read_b128 v[36:39], v179 offset:32
	ds_read_b128 v[40:43], v179 offset:64
	ds_read_b128 v[44:47], v179 offset:96
	ds_read_b128 v[48:51], v175 offset:16384
	ds_read_b128 v[52:55], v176 offset:16384
	ds_read_b128 v[56:59], v177 offset:16384
	ds_read_b128 v[60:63], v178 offset:16384
	ds_read_b128 v[80:83], v179 offset:128
	ds_read_b128 v[84:87], v179 offset:160
	ds_read_b128 v[88:91], v179 offset:192
	ds_read_b128 v[92:95], v179 offset:224
	s_waitcnt lgkmcnt(7)
	v_mfma_f32_32x32x16_bf16 v[32:47], v[48:51], v[96:99], v[32:47]
	ds_read_b128 v[64:67], v175 offset:20480
	s_waitcnt lgkmcnt(7)
	v_mfma_f32_32x32x16_bf16 v[32:47], v[52:55], v[100:103], v[32:47]
	ds_read_b128 v[68:71], v176 offset:20480
	s_waitcnt lgkmcnt(7)
	v_mfma_f32_32x32x16_bf16 v[32:47], v[56:59], v[104:107], v[32:47]
	ds_read_b128 v[72:75], v177 offset:20480
	s_waitcnt lgkmcnt(7)
	v_mfma_f32_32x32x16_bf16 v[32:47], v[60:63], v[108:111], v[32:47]
	ds_read_b128 v[76:79], v178 offset:20480
	ds_read_b128 v[48:51], v179 offset:256
	ds_read_b128 v[52:55], v179 offset:288
	ds_read_b128 v[56:59], v179 offset:320
	ds_read_b128 v[60:63], v179 offset:352
	s_waitcnt lgkmcnt(7)
	v_mfma_f32_32x32x16_bf16 v[80:95], v[64:67], v[96:99], v[80:95]
	ds_read_b128 v[202:205], v175 offset:24576
	s_waitcnt lgkmcnt(7)
	v_mfma_f32_32x32x16_bf16 v[80:95], v[68:71], v[100:103], v[80:95]
	ds_read_b128 v[206:209], v176 offset:24576
	s_waitcnt lgkmcnt(7)
	v_mfma_f32_32x32x16_bf16 v[80:95], v[72:75], v[104:107], v[80:95]
	ds_read_b128 v[210:213], v177 offset:24576
	s_waitcnt lgkmcnt(7)
	v_mfma_f32_32x32x16_bf16 v[80:95], v[76:79], v[108:111], v[80:95]
	ds_read_b128 v[214:217], v178 offset:24576
	ds_read_b128 v[64:67], v179 offset:384
	ds_read_b128 v[68:71], v179 offset:416
	ds_read_b128 v[72:75], v179 offset:448
	ds_read_b128 v[76:79], v179 offset:480
	ds_read_b128 v[218:221], v175 offset:28672
	v_max3_f32 v222, v32, v33, v34
	v_max3_f32 v222, v222, v35, v36
	v_max3_f32 v222, v222, v37, v38
	v_max3_f32 v222, v222, v39, v40
	v_max3_f32 v222, v222, v41, v42
	v_max3_f32 v222, v222, v43, v44
	v_max3_f32 v222, v222, v45, v46
	s_waitcnt lgkmcnt(8)
	v_mfma_f32_32x32x16_bf16 v[48:63], v[202:205], v[96:99], v[48:63]
	ds_read_b128 v[202:205], v176 offset:28672
	s_waitcnt lgkmcnt(8)
	v_mfma_f32_32x32x16_bf16 v[48:63], v[206:209], v[100:103], v[48:63]
	ds_read_b128 v[206:209], v177 offset:28672
	s_waitcnt lgkmcnt(8)
	v_mfma_f32_32x32x16_bf16 v[48:63], v[210:213], v[104:107], v[48:63]
	ds_read_b128 v[210:213], v178 offset:28672
	s_waitcnt lgkmcnt(8)
	v_mfma_f32_32x32x16_bf16 v[48:63], v[214:217], v[108:111], v[48:63]
	v_max3_f32 v222, v222, v47, v80
	v_max3_f32 v222, v222, v81, v82
	v_max3_f32 v222, v222, v83, v84
	v_max3_f32 v222, v222, v85, v86
	v_max3_f32 v222, v222, v87, v88
	v_max3_f32 v222, v222, v89, v90
	v_max3_f32 v222, v222, v91, v92
	v_max3_f32 v222, v222, v93, v94
	s_waitcnt lgkmcnt(3)
	v_mfma_f32_32x32x16_bf16 v[64:79], v[218:221], v[96:99], v[64:79]
	s_waitcnt lgkmcnt(2)
	v_mfma_f32_32x32x16_bf16 v[64:79], v[202:205], v[100:103], v[64:79]
	s_waitcnt lgkmcnt(1)
	v_mfma_f32_32x32x16_bf16 v[64:79], v[206:209], v[104:107], v[64:79]
	s_waitcnt lgkmcnt(0)
	v_mfma_f32_32x32x16_bf16 v[64:79], v[210:213], v[108:111], v[64:79]
	v_add_u32_e32 v218, 0xc000, v181
	ds_read_b64_tr_b16 v[202:203], v218 offset:0
	ds_read_b64_tr_b16 v[204:205], v218 offset:1536
	ds_read_b64_tr_b16 v[206:207], v218 offset:64
	ds_read_b64_tr_b16 v[208:209], v218 offset:1600
	ds_read_b64_tr_b16 v[210:211], v218 offset:3072
	ds_read_b64_tr_b16 v[212:213], v218 offset:4608
	ds_read_b64_tr_b16 v[214:215], v218 offset:3136
	ds_read_b64_tr_b16 v[216:217], v218 offset:4672
	v_max3_f32 v222, v222, v95, v48
	v_max3_f32 v222, v222, v49, v50
	v_max3_f32 v222, v222, v51, v52
	v_max3_f32 v222, v222, v53, v54
	v_max3_f32 v222, v222, v55, v56
	v_max3_f32 v222, v222, v57, v58
	v_max3_f32 v222, v222, v59, v60
	v_max3_f32 v222, v222, v61, v62
	v_cmp_gt_i32_e64 vcc, 0, v150
	v_cmp_gt_i32_e64 s[2:3], 1, v150
	v_cmp_gt_i32_e64 s[46:47], 2, v150
	v_cndmask_b32_e64 v64, v64, v228, vcc
	v_cmp_gt_i32_e64 vcc, 3, v150
	v_cndmask_b32_e64 v65, v65, v228, s[2:3]
	v_cmp_gt_i32_e64 s[2:3], 8, v150
	v_cndmask_b32_e64 v66, v66, v228, s[46:47]
	v_cmp_gt_i32_e64 s[46:47], 9, v150
	v_cndmask_b32_e64 v67, v67, v228, vcc
	v_cmp_gt_i32_e64 vcc, 10, v150
	v_cndmask_b32_e64 v68, v68, v228, s[2:3]
	v_cmp_gt_i32_e64 s[2:3], 11, v150
	v_cndmask_b32_e64 v69, v69, v228, s[46:47]
	v_cmp_gt_i32_e64 s[46:47], 16, v150
	v_cndmask_b32_e64 v70, v70, v228, vcc
	v_cmp_gt_i32_e64 vcc, 17, v150
	v_cndmask_b32_e64 v71, v71, v228, s[2:3]
	v_cmp_gt_i32_e64 s[2:3], 18, v150
	v_cndmask_b32_e64 v72, v72, v228, s[46:47]
	v_cmp_gt_i32_e64 s[46:47], 19, v150
	v_cndmask_b32_e64 v73, v73, v228, vcc
	v_cmp_gt_i32_e64 vcc, 24, v150
	v_cndmask_b32_e64 v74, v74, v228, s[2:3]
	v_cmp_gt_i32_e64 s[2:3], 25, v150
	v_cndmask_b32_e64 v75, v75, v228, s[46:47]
	v_cmp_gt_i32_e64 s[46:47], 26, v150
	v_cndmask_b32_e64 v76, v76, v228, vcc
	v_cmp_gt_i32_e64 vcc, 27, v150
	v_cndmask_b32_e64 v77, v77, v228, s[2:3]
	v_cndmask_b32_e64 v78, v78, v228, s[46:47]
	v_cndmask_b32_e64 v79, v79, v228, vcc
	v_max3_f32 v222, v222, v63, v64
	v_max3_f32 v222, v222, v65, v66
	v_max3_f32 v222, v222, v67, v68
	v_max3_f32 v222, v222, v69, v70
	v_max3_f32 v222, v222, v71, v72
	v_max3_f32 v222, v222, v73, v74
	v_max3_f32 v222, v222, v75, v76
	v_max3_f32 v222, v222, v77, v78
	v_max_f32_e32 v222, v222, v79
	ds_bpermute_b32 v183, v151, v222
	s_waitcnt lgkmcnt(0)
	v_max_f32_e32 v183, v183, v183
	v_max_f32_e32 v182, v222, v183
	v_sub_f32_e32 v182, v182, v161
	v_add_f32_e32 v183, 0x40c00000, v164
	v_cmp_gt_f32_e32 vcc, v182, v183
	s_cbranch_vccz .Lfox_b0d3_pv
	v_max_f32_e32 v182, v182, v182
	v_max_f32_e32 v183, v164, v164
	v_max_f32_e32 v182, v183, v182
	v_sub_f32_e32 v164, v164, v182
	v_exp_f32_e32 v164, v164
	s_nop 0
	v_mul_f32_e32 v163, v163, v164
	v_pk_mul_f32 v[30:31], v[30:31], v[164:165] op_sel_hi:[1,0]
	v_pk_mul_f32 v[28:29], v[28:29], v[164:165] op_sel_hi:[1,0]
	v_pk_mul_f32 v[26:27], v[26:27], v[164:165] op_sel_hi:[1,0]
	v_pk_mul_f32 v[24:25], v[24:25], v[164:165] op_sel_hi:[1,0]
	v_pk_mul_f32 v[22:23], v[22:23], v[164:165] op_sel_hi:[1,0]
	v_pk_mul_f32 v[20:21], v[20:21], v[164:165] op_sel_hi:[1,0]
	v_pk_mul_f32 v[18:19], v[18:19], v[164:165] op_sel_hi:[1,0]
	v_pk_mul_f32 v[16:17], v[16:17], v[164:165] op_sel_hi:[1,0]
	v_pk_mul_f32 v[14:15], v[14:15], v[164:165] op_sel_hi:[1,0]
	v_pk_mul_f32 v[12:13], v[12:13], v[164:165] op_sel_hi:[1,0]
	v_pk_mul_f32 v[10:11], v[10:11], v[164:165] op_sel_hi:[1,0]
	v_pk_mul_f32 v[8:9], v[8:9], v[164:165] op_sel_hi:[1,0]
	v_pk_mul_f32 v[6:7], v[6:7], v[164:165] op_sel_hi:[1,0]
	v_pk_mul_f32 v[4:5], v[4:5], v[164:165] op_sel_hi:[1,0]
	v_pk_mul_f32 v[2:3], v[2:3], v[164:165] op_sel_hi:[1,0]
	v_pk_mul_f32 v[0:1], v[0:1], v[164:165] op_sel_hi:[1,0]
	v_mov_b32_e32 v164, v182
.Lfox_b0d3_pv:
	v_sub_f32_e64 v222, -v161, v164
	v_add_f32_e32 v32, v32, v222
	v_add_f32_e32 v33, v33, v222
	v_add_f32_e32 v34, v34, v222
	v_add_f32_e32 v35, v35, v222
	v_add_f32_e32 v36, v36, v222
	v_add_f32_e32 v37, v37, v222
	v_add_f32_e32 v38, v38, v222
	v_add_f32_e32 v39, v39, v222
	v_exp_f32_e32 v32, v32
	v_exp_f32_e32 v33, v33
	v_exp_f32_e32 v34, v34
	v_exp_f32_e32 v35, v35
	v_exp_f32_e32 v36, v36
	v_exp_f32_e32 v37, v37
	v_exp_f32_e32 v38, v38
	v_exp_f32_e32 v39, v39
	v_add_f32_e32 v182, v32, v33
	v_add_f32_e32 v183, v34, v35
	v_add_f32_e32 v182, v182, v36
	v_add_f32_e32 v183, v183, v37
	v_add_f32_e32 v182, v182, v38
	v_add_f32_e32 v183, v183, v39
	v_cvt_pk_bf16_f32 v32, v32, v33
	v_cvt_pk_bf16_f32 v33, v34, v35
	v_cvt_pk_bf16_f32 v34, v36, v37
	v_cvt_pk_bf16_f32 v35, v38, v39
	s_nop 1
	v_mfma_f32_32x32x16_bf16 v[16:31], v[202:205], v[32:35], v[16:31]
	v_add_f32_e32 v40, v40, v222
	v_add_f32_e32 v41, v41, v222
	v_add_f32_e32 v42, v42, v222
	v_add_f32_e32 v43, v43, v222
	v_add_f32_e32 v44, v44, v222
	v_add_f32_e32 v45, v45, v222
	v_add_f32_e32 v46, v46, v222
	v_add_f32_e32 v47, v47, v222
	v_exp_f32_e32 v40, v40
	v_exp_f32_e32 v41, v41
	v_exp_f32_e32 v42, v42
	v_exp_f32_e32 v43, v43
	v_exp_f32_e32 v44, v44
	v_exp_f32_e32 v45, v45
	v_exp_f32_e32 v46, v46
	v_exp_f32_e32 v47, v47
	v_mfma_f32_32x32x16_bf16 v[0:15], v[206:209], v[32:35], v[0:15]
	ds_read_b64_tr_b16 v[202:203], v218 offset:6144
	ds_read_b64_tr_b16 v[204:205], v218 offset:7680
	ds_read_b64_tr_b16 v[206:207], v218 offset:6208
	ds_read_b64_tr_b16 v[208:209], v218 offset:7744
	v_add_f32_e32 v182, v182, v40
	v_add_f32_e32 v183, v183, v41
	v_add_f32_e32 v182, v182, v42
	v_add_f32_e32 v183, v183, v43
	v_add_f32_e32 v182, v182, v44
	v_add_f32_e32 v183, v183, v45
	v_add_f32_e32 v182, v182, v46
	v_add_f32_e32 v183, v183, v47
	v_cvt_pk_bf16_f32 v40, v40, v41
	v_cvt_pk_bf16_f32 v41, v42, v43
	v_cvt_pk_bf16_f32 v42, v44, v45
	v_cvt_pk_bf16_f32 v43, v46, v47
	s_nop 1
	v_mfma_f32_32x32x16_bf16 v[16:31], v[210:213], v[40:43], v[16:31]
	v_add_f32_e32 v80, v80, v222
	v_add_f32_e32 v81, v81, v222
	v_add_f32_e32 v82, v82, v222
	v_add_f32_e32 v83, v83, v222
	v_add_f32_e32 v84, v84, v222
	v_add_f32_e32 v85, v85, v222
	v_add_f32_e32 v86, v86, v222
	v_add_f32_e32 v87, v87, v222
	v_exp_f32_e32 v80, v80
	v_exp_f32_e32 v81, v81
	v_exp_f32_e32 v82, v82
	v_exp_f32_e32 v83, v83
	v_exp_f32_e32 v84, v84
	v_exp_f32_e32 v85, v85
	v_exp_f32_e32 v86, v86
	v_exp_f32_e32 v87, v87
	v_mfma_f32_32x32x16_bf16 v[0:15], v[214:217], v[40:43], v[0:15]
	ds_read_b64_tr_b16 v[210:211], v218 offset:9216
	ds_read_b64_tr_b16 v[212:213], v218 offset:10752
	ds_read_b64_tr_b16 v[214:215], v218 offset:9280
	ds_read_b64_tr_b16 v[216:217], v218 offset:10816
	v_add_f32_e32 v182, v182, v80
	v_add_f32_e32 v183, v183, v81
	v_add_f32_e32 v182, v182, v82
	v_add_f32_e32 v183, v183, v83
	v_add_f32_e32 v182, v182, v84
	v_add_f32_e32 v183, v183, v85
	v_add_f32_e32 v182, v182, v86
	v_add_f32_e32 v183, v183, v87
	v_cvt_pk_bf16_f32 v80, v80, v81
	v_cvt_pk_bf16_f32 v81, v82, v83
	v_cvt_pk_bf16_f32 v82, v84, v85
	v_cvt_pk_bf16_f32 v83, v86, v87
	s_waitcnt lgkmcnt(6)
	s_nop 0
	v_mfma_f32_32x32x16_bf16 v[16:31], v[202:205], v[80:83], v[16:31]
	v_add_f32_e32 v88, v88, v222
	v_add_f32_e32 v89, v89, v222
	v_add_f32_e32 v90, v90, v222
	v_add_f32_e32 v91, v91, v222
	v_add_f32_e32 v92, v92, v222
	v_add_f32_e32 v93, v93, v222
	v_add_f32_e32 v94, v94, v222
	v_add_f32_e32 v95, v95, v222
	v_exp_f32_e32 v88, v88
	v_exp_f32_e32 v89, v89
	v_exp_f32_e32 v90, v90
	v_exp_f32_e32 v91, v91
	v_exp_f32_e32 v92, v92
	v_exp_f32_e32 v93, v93
	v_exp_f32_e32 v94, v94
	v_exp_f32_e32 v95, v95
	s_waitcnt lgkmcnt(4)
	v_mfma_f32_32x32x16_bf16 v[0:15], v[206:209], v[80:83], v[0:15]
	ds_read_b64_tr_b16 v[202:203], v218 offset:12288
	ds_read_b64_tr_b16 v[204:205], v218 offset:13824
	ds_read_b64_tr_b16 v[206:207], v218 offset:12352
	ds_read_b64_tr_b16 v[208:209], v218 offset:13888
	v_add_f32_e32 v182, v182, v88
	v_add_f32_e32 v183, v183, v89
	v_add_f32_e32 v182, v182, v90
	v_add_f32_e32 v183, v183, v91
	v_add_f32_e32 v182, v182, v92
	v_add_f32_e32 v183, v183, v93
	v_add_f32_e32 v182, v182, v94
	v_add_f32_e32 v183, v183, v95
	v_cvt_pk_bf16_f32 v88, v88, v89
	v_cvt_pk_bf16_f32 v89, v90, v91
	v_cvt_pk_bf16_f32 v90, v92, v93
	v_cvt_pk_bf16_f32 v91, v94, v95
	s_waitcnt lgkmcnt(6)
	s_nop 0
	v_mfma_f32_32x32x16_bf16 v[16:31], v[210:213], v[88:91], v[16:31]
	v_add_f32_e32 v48, v48, v222
	v_add_f32_e32 v49, v49, v222
	v_add_f32_e32 v50, v50, v222
	v_add_f32_e32 v51, v51, v222
	v_add_f32_e32 v52, v52, v222
	v_add_f32_e32 v53, v53, v222
	v_add_f32_e32 v54, v54, v222
	v_add_f32_e32 v55, v55, v222
	v_exp_f32_e32 v48, v48
	v_exp_f32_e32 v49, v49
	v_exp_f32_e32 v50, v50
	v_exp_f32_e32 v51, v51
	v_exp_f32_e32 v52, v52
	v_exp_f32_e32 v53, v53
	v_exp_f32_e32 v54, v54
	v_exp_f32_e32 v55, v55
	s_waitcnt lgkmcnt(4)
	v_mfma_f32_32x32x16_bf16 v[0:15], v[214:217], v[88:91], v[0:15]
	ds_read_b64_tr_b16 v[210:211], v218 offset:15360
	ds_read_b64_tr_b16 v[212:213], v218 offset:16896
	ds_read_b64_tr_b16 v[214:215], v218 offset:15424
	ds_read_b64_tr_b16 v[216:217], v218 offset:16960
	v_add_f32_e32 v182, v182, v48
	v_add_f32_e32 v183, v183, v49
	v_add_f32_e32 v182, v182, v50
	v_add_f32_e32 v183, v183, v51
	v_add_f32_e32 v182, v182, v52
	v_add_f32_e32 v183, v183, v53
	v_add_f32_e32 v182, v182, v54
	v_add_f32_e32 v183, v183, v55
	v_cvt_pk_bf16_f32 v48, v48, v49
	v_cvt_pk_bf16_f32 v49, v50, v51
	v_cvt_pk_bf16_f32 v50, v52, v53
	v_cvt_pk_bf16_f32 v51, v54, v55
	s_waitcnt lgkmcnt(6)
	s_nop 0
	v_mfma_f32_32x32x16_bf16 v[16:31], v[202:205], v[48:51], v[16:31]
	v_add_f32_e32 v56, v56, v222
	v_add_f32_e32 v57, v57, v222
	v_add_f32_e32 v58, v58, v222
	v_add_f32_e32 v59, v59, v222
	v_add_f32_e32 v60, v60, v222
	v_add_f32_e32 v61, v61, v222
	v_add_f32_e32 v62, v62, v222
	v_add_f32_e32 v63, v63, v222
	v_exp_f32_e32 v56, v56
	v_exp_f32_e32 v57, v57
	v_exp_f32_e32 v58, v58
	v_exp_f32_e32 v59, v59
	v_exp_f32_e32 v60, v60
	v_exp_f32_e32 v61, v61
	v_exp_f32_e32 v62, v62
	v_exp_f32_e32 v63, v63
	s_waitcnt lgkmcnt(4)
	v_mfma_f32_32x32x16_bf16 v[0:15], v[206:209], v[48:51], v[0:15]
	ds_read_b64_tr_b16 v[202:203], v218 offset:18432
	ds_read_b64_tr_b16 v[204:205], v218 offset:19968
	ds_read_b64_tr_b16 v[206:207], v218 offset:18496
	ds_read_b64_tr_b16 v[208:209], v218 offset:20032
	v_add_f32_e32 v182, v182, v56
	v_add_f32_e32 v183, v183, v57
	v_add_f32_e32 v182, v182, v58
	v_add_f32_e32 v183, v183, v59
	v_add_f32_e32 v182, v182, v60
	v_add_f32_e32 v183, v183, v61
	v_add_f32_e32 v182, v182, v62
	v_add_f32_e32 v183, v183, v63
	v_cvt_pk_bf16_f32 v56, v56, v57
	v_cvt_pk_bf16_f32 v57, v58, v59
	v_cvt_pk_bf16_f32 v58, v60, v61
	v_cvt_pk_bf16_f32 v59, v62, v63
	s_waitcnt lgkmcnt(6)
	s_nop 0
	v_mfma_f32_32x32x16_bf16 v[16:31], v[210:213], v[56:59], v[16:31]
	v_add_f32_e32 v64, v64, v222
	v_add_f32_e32 v65, v65, v222
	v_add_f32_e32 v66, v66, v222
	v_add_f32_e32 v67, v67, v222
	v_add_f32_e32 v68, v68, v222
	v_add_f32_e32 v69, v69, v222
	v_add_f32_e32 v70, v70, v222
	v_add_f32_e32 v71, v71, v222
	v_exp_f32_e32 v64, v64
	v_exp_f32_e32 v65, v65
	v_exp_f32_e32 v66, v66
	v_exp_f32_e32 v67, v67
	v_exp_f32_e32 v68, v68
	v_exp_f32_e32 v69, v69
	v_exp_f32_e32 v70, v70
	v_exp_f32_e32 v71, v71
	s_waitcnt lgkmcnt(4)
	v_mfma_f32_32x32x16_bf16 v[0:15], v[214:217], v[56:59], v[0:15]
	ds_read_b64_tr_b16 v[210:211], v218 offset:21504
	ds_read_b64_tr_b16 v[212:213], v218 offset:23040
	ds_read_b64_tr_b16 v[214:215], v218 offset:21568
	ds_read_b64_tr_b16 v[216:217], v218 offset:23104
	v_add_f32_e32 v182, v182, v64
	v_add_f32_e32 v183, v183, v65
	v_add_f32_e32 v182, v182, v66
	v_add_f32_e32 v183, v183, v67
	v_add_f32_e32 v182, v182, v68
	v_add_f32_e32 v183, v183, v69
	v_add_f32_e32 v182, v182, v70
	v_add_f32_e32 v183, v183, v71
	v_cvt_pk_bf16_f32 v64, v64, v65
	v_cvt_pk_bf16_f32 v65, v66, v67
	v_cvt_pk_bf16_f32 v66, v68, v69
	v_cvt_pk_bf16_f32 v67, v70, v71
	s_waitcnt lgkmcnt(6)
	s_nop 0
	v_mfma_f32_32x32x16_bf16 v[16:31], v[202:205], v[64:67], v[16:31]
	v_add_f32_e32 v72, v72, v222
	v_add_f32_e32 v73, v73, v222
	v_add_f32_e32 v74, v74, v222
	v_add_f32_e32 v75, v75, v222
	v_add_f32_e32 v76, v76, v222
	v_add_f32_e32 v77, v77, v222
	v_add_f32_e32 v78, v78, v222
	v_add_f32_e32 v79, v79, v222
	v_exp_f32_e32 v72, v72
	v_exp_f32_e32 v73, v73
	v_exp_f32_e32 v74, v74
	v_exp_f32_e32 v75, v75
	v_exp_f32_e32 v76, v76
	v_exp_f32_e32 v77, v77
	v_exp_f32_e32 v78, v78
	v_exp_f32_e32 v79, v79
	s_waitcnt lgkmcnt(4)
	v_mfma_f32_32x32x16_bf16 v[0:15], v[206:209], v[64:67], v[0:15]
	v_add_f32_e32 v182, v182, v72
	v_add_f32_e32 v183, v183, v73
	v_add_f32_e32 v182, v182, v74
	v_add_f32_e32 v183, v183, v75
	v_add_f32_e32 v182, v182, v76
	v_add_f32_e32 v183, v183, v77
	v_add_f32_e32 v182, v182, v78
	v_add_f32_e32 v183, v183, v79
	v_cvt_pk_bf16_f32 v72, v72, v73
	v_cvt_pk_bf16_f32 v73, v74, v75
	v_cvt_pk_bf16_f32 v74, v76, v77
	v_cvt_pk_bf16_f32 v75, v78, v79
	s_waitcnt lgkmcnt(2)
	s_nop 0
	v_mfma_f32_32x32x16_bf16 v[16:31], v[210:213], v[72:75], v[16:31]
	s_waitcnt lgkmcnt(0)
	v_mfma_f32_32x32x16_bf16 v[0:15], v[214:217], v[72:75], v[0:15]
	v_add_f32_e32 v163, v163, v182
	v_add_f32_e32 v163, v163, v183
	s_waitcnt vmcnt(3)
	ds_write_b128 v147, v[112:115] offset:32768
	s_waitcnt vmcnt(1)
	ds_write_b128 v147, v[120:123] offset:40960
	v_add_u32_e32 v222, 0x12000, v153
	ds_write_b128 v222, v[116:119]
	s_waitcnt vmcnt(0)
	ds_write_b128 v222, v[124:127] offset:12288
	s_waitcnt lgkmcnt(0)
	s_barrier
	s_branch .Lfox_band1
.Lfox_b0d4:
	v_lshl_add_u64 v[112:113], v[158:159], 0, s[36:37]
	v_add_co_u32_e32 v116, vcc, 0x70f1000, v112
	s_nop 1
	v_addc_co_u32_e32 v117, vcc, 0, v113, vcc
	v_add_co_u32_e32 v182, vcc, 0x7169000, v112
	s_nop 1
	v_addc_co_u32_e32 v183, vcc, 0, v113, vcc
	global_load_dwordx4 v[112:115], v[116:117], off offset:512
	s_nop 0
	global_load_dwordx4 v[116:119], v[116:117], off offset:1536
	global_load_dwordx4 v[120:123], v[182:183], off offset:512
	global_load_dwordx4 v[124:127], v[182:183], off offset:1536
	ds_read_b128 v[32:35], v179
	ds_read_b128 v[36:39], v179 offset:32
	ds_read_b128 v[40:43], v179 offset:64
	ds_read_b128 v[44:47], v179 offset:96
	ds_read_b128 v[48:51], v175 offset:16384
	ds_read_b128 v[52:55], v176 offset:16384
	ds_read_b128 v[56:59], v177 offset:16384
	ds_read_b128 v[60:63], v178 offset:16384
	ds_read_b128 v[80:83], v179 offset:128
	ds_read_b128 v[84:87], v179 offset:160
	ds_read_b128 v[88:91], v179 offset:192
	ds_read_b128 v[92:95], v179 offset:224
	s_waitcnt lgkmcnt(7)
	v_mfma_f32_32x32x16_bf16 v[32:47], v[48:51], v[96:99], v[32:47]
	ds_read_b128 v[64:67], v175 offset:20480
	s_waitcnt lgkmcnt(7)
	v_mfma_f32_32x32x16_bf16 v[32:47], v[52:55], v[100:103], v[32:47]
	ds_read_b128 v[68:71], v176 offset:20480
	s_waitcnt lgkmcnt(7)
	v_mfma_f32_32x32x16_bf16 v[32:47], v[56:59], v[104:107], v[32:47]
	ds_read_b128 v[72:75], v177 offset:20480
	s_waitcnt lgkmcnt(7)
	v_mfma_f32_32x32x16_bf16 v[32:47], v[60:63], v[108:111], v[32:47]
	ds_read_b128 v[76:79], v178 offset:20480
	ds_read_b128 v[48:51], v179 offset:256
	ds_read_b128 v[52:55], v179 offset:288
	ds_read_b128 v[56:59], v179 offset:320
	ds_read_b128 v[60:63], v179 offset:352
	s_waitcnt lgkmcnt(7)
	v_mfma_f32_32x32x16_bf16 v[80:95], v[64:67], v[96:99], v[80:95]
	ds_read_b128 v[202:205], v175 offset:24576
	s_waitcnt lgkmcnt(7)
	v_mfma_f32_32x32x16_bf16 v[80:95], v[68:71], v[100:103], v[80:95]
	ds_read_b128 v[206:209], v176 offset:24576
	s_waitcnt lgkmcnt(7)
	v_mfma_f32_32x32x16_bf16 v[80:95], v[72:75], v[104:107], v[80:95]
	ds_read_b128 v[210:213], v177 offset:24576
	s_waitcnt lgkmcnt(7)
	v_mfma_f32_32x32x16_bf16 v[80:95], v[76:79], v[108:111], v[80:95]
	ds_read_b128 v[214:217], v178 offset:24576
	ds_read_b128 v[64:67], v179 offset:384
	ds_read_b128 v[68:71], v179 offset:416
	ds_read_b128 v[72:75], v179 offset:448
	ds_read_b128 v[76:79], v179 offset:480
	ds_read_b128 v[218:221], v175 offset:28672
	v_max3_f32 v222, v32, v33, v34
	v_max3_f32 v222, v222, v35, v36
	v_max3_f32 v222, v222, v37, v38
	v_max3_f32 v222, v222, v39, v40
	v_max3_f32 v222, v222, v41, v42
	v_max3_f32 v222, v222, v43, v44
	v_max3_f32 v222, v222, v45, v46
	s_waitcnt lgkmcnt(8)
	v_mfma_f32_32x32x16_bf16 v[48:63], v[202:205], v[96:99], v[48:63]
	ds_read_b128 v[202:205], v176 offset:28672
	s_waitcnt lgkmcnt(8)
	v_mfma_f32_32x32x16_bf16 v[48:63], v[206:209], v[100:103], v[48:63]
	ds_read_b128 v[206:209], v177 offset:28672
	s_waitcnt lgkmcnt(8)
	v_mfma_f32_32x32x16_bf16 v[48:63], v[210:213], v[104:107], v[48:63]
	ds_read_b128 v[210:213], v178 offset:28672
	s_waitcnt lgkmcnt(8)
	v_mfma_f32_32x32x16_bf16 v[48:63], v[214:217], v[108:111], v[48:63]
	v_max3_f32 v222, v222, v47, v80
	v_max3_f32 v222, v222, v81, v82
	v_max3_f32 v222, v222, v83, v84
	v_max3_f32 v222, v222, v85, v86
	v_max3_f32 v222, v222, v87, v88
	v_max3_f32 v222, v222, v89, v90
	v_max3_f32 v222, v222, v91, v92
	v_max3_f32 v222, v222, v93, v94
	s_waitcnt lgkmcnt(3)
	v_mfma_f32_32x32x16_bf16 v[64:79], v[218:221], v[96:99], v[64:79]
	s_waitcnt lgkmcnt(2)
	v_mfma_f32_32x32x16_bf16 v[64:79], v[202:205], v[100:103], v[64:79]
	s_waitcnt lgkmcnt(1)
	v_mfma_f32_32x32x16_bf16 v[64:79], v[206:209], v[104:107], v[64:79]
	s_waitcnt lgkmcnt(0)
	v_mfma_f32_32x32x16_bf16 v[64:79], v[210:213], v[108:111], v[64:79]
	v_add_u32_e32 v218, 0xc000, v181
	ds_read_b64_tr_b16 v[202:203], v218 offset:0
	ds_read_b64_tr_b16 v[204:205], v218 offset:1536
	ds_read_b64_tr_b16 v[206:207], v218 offset:64
	ds_read_b64_tr_b16 v[208:209], v218 offset:1600
	ds_read_b64_tr_b16 v[210:211], v218 offset:3072
	ds_read_b64_tr_b16 v[212:213], v218 offset:4608
	ds_read_b64_tr_b16 v[214:215], v218 offset:3136
	ds_read_b64_tr_b16 v[216:217], v218 offset:4672
	v_max3_f32 v222, v222, v95, v48
	v_max3_f32 v222, v222, v49, v50
	v_max3_f32 v222, v222, v51, v52
	v_max3_f32 v222, v222, v53, v54
	v_max3_f32 v222, v222, v55, v56
	v_max3_f32 v222, v222, v57, v58
	v_max3_f32 v222, v222, v59, v60
	v_max3_f32 v222, v222, v61, v62
	v_max3_f32 v222, v222, v63, v64
	v_max3_f32 v222, v222, v65, v66
	v_max3_f32 v222, v222, v67, v68
	v_max3_f32 v222, v222, v69, v70
	v_max3_f32 v222, v222, v71, v72
	v_max3_f32 v222, v222, v73, v74
	v_max3_f32 v222, v222, v75, v76
	v_max3_f32 v222, v222, v77, v78
	v_max_f32_e32 v222, v222, v79
	ds_bpermute_b32 v183, v151, v222
	s_waitcnt lgkmcnt(0)
	v_max_f32_e32 v183, v183, v183
	v_max_f32_e32 v182, v222, v183
	v_sub_f32_e32 v182, v182, v161
	v_add_f32_e32 v183, 0x40c00000, v164
	v_cmp_gt_f32_e32 vcc, v182, v183
	s_cbranch_vccz .Lfox_b0d4_pv
	v_max_f32_e32 v182, v182, v182
	v_max_f32_e32 v183, v164, v164
	v_max_f32_e32 v182, v183, v182
	v_sub_f32_e32 v164, v164, v182
	v_exp_f32_e32 v164, v164
	s_nop 0
	v_mul_f32_e32 v163, v163, v164
	v_pk_mul_f32 v[30:31], v[30:31], v[164:165] op_sel_hi:[1,0]
	v_pk_mul_f32 v[28:29], v[28:29], v[164:165] op_sel_hi:[1,0]
	v_pk_mul_f32 v[26:27], v[26:27], v[164:165] op_sel_hi:[1,0]
	v_pk_mul_f32 v[24:25], v[24:25], v[164:165] op_sel_hi:[1,0]
	v_pk_mul_f32 v[22:23], v[22:23], v[164:165] op_sel_hi:[1,0]
	v_pk_mul_f32 v[20:21], v[20:21], v[164:165] op_sel_hi:[1,0]
	v_pk_mul_f32 v[18:19], v[18:19], v[164:165] op_sel_hi:[1,0]
	v_pk_mul_f32 v[16:17], v[16:17], v[164:165] op_sel_hi:[1,0]
	v_pk_mul_f32 v[14:15], v[14:15], v[164:165] op_sel_hi:[1,0]
	v_pk_mul_f32 v[12:13], v[12:13], v[164:165] op_sel_hi:[1,0]
	v_pk_mul_f32 v[10:11], v[10:11], v[164:165] op_sel_hi:[1,0]
	v_pk_mul_f32 v[8:9], v[8:9], v[164:165] op_sel_hi:[1,0]
	v_pk_mul_f32 v[6:7], v[6:7], v[164:165] op_sel_hi:[1,0]
	v_pk_mul_f32 v[4:5], v[4:5], v[164:165] op_sel_hi:[1,0]
	v_pk_mul_f32 v[2:3], v[2:3], v[164:165] op_sel_hi:[1,0]
	v_pk_mul_f32 v[0:1], v[0:1], v[164:165] op_sel_hi:[1,0]
	v_mov_b32_e32 v164, v182

.Lfox_band1:
	s_cmp_lt_u32 s51, 4
	s_cbranch_scc1 .Lfox_band_done
	s_cmp_eq_u32 s51, 7
	s_cbranch_scc1 .Lfox_b1d3
	s_cmp_eq_u32 s51, 6
	s_cbranch_scc1 .Lfox_b1d2
	s_cmp_eq_u32 s51, 5
	s_cbranch_scc1 .Lfox_b1d1
.Lfox_b1d0:
	ds_read_b128 v[32:35], v179 offset:512
	ds_read_b128 v[36:39], v179 offset:544
	ds_read_b128 v[40:43], v179 offset:576
	ds_read_b128 v[44:47], v179 offset:608
	ds_read_b128 v[48:51], v175 offset:32768
	ds_read_b128 v[52:55], v176 offset:32768
	ds_read_b128 v[56:59], v177 offset:32768
	ds_read_b128 v[60:63], v178 offset:32768
	s_waitcnt lgkmcnt(3)
	v_mfma_f32_32x32x16_bf16 v[32:47], v[48:51], v[96:99], v[32:47]
	s_waitcnt lgkmcnt(2)
	v_mfma_f32_32x32x16_bf16 v[32:47], v[52:55], v[100:103], v[32:47]
	s_waitcnt lgkmcnt(1)
	v_mfma_f32_32x32x16_bf16 v[32:47], v[56:59], v[104:107], v[32:47]
	s_waitcnt lgkmcnt(0)
	v_mfma_f32_32x32x16_bf16 v[32:47], v[60:63], v[108:111], v[32:47]
	v_add_u32_e32 v218, 0x12000, v181
	ds_read_b64_tr_b16 v[202:203], v218 offset:0
	ds_read_b64_tr_b16 v[204:205], v218 offset:1536
	ds_read_b64_tr_b16 v[206:207], v218 offset:64
	ds_read_b64_tr_b16 v[208:209], v218 offset:1600
	ds_read_b64_tr_b16 v[210:211], v218 offset:3072
	ds_read_b64_tr_b16 v[212:213], v218 offset:4608
	ds_read_b64_tr_b16 v[214:215], v218 offset:3136
	ds_read_b64_tr_b16 v[216:217], v218 offset:4672
	v_cmp_gt_i32_e64 vcc, 0, v150
	v_cmp_gt_i32_e64 s[2:3], 1, v150
	v_cmp_gt_i32_e64 s[46:47], 2, v150
	v_cndmask_b32_e64 v32, v32, v228, vcc
	v_cmp_gt_i32_e64 vcc, 3, v150
	v_cndmask_b32_e64 v33, v33, v228, s[2:3]
	v_cmp_gt_i32_e64 s[2:3], 8, v150
	v_cndmask_b32_e64 v34, v34, v228, s[46:47]
	v_cmp_gt_i32_e64 s[46:47], 9, v150
	v_cndmask_b32_e64 v35, v35, v228, vcc
	v_cmp_gt_i32_e64 vcc, 10, v150
	v_cndmask_b32_e64 v36, v36, v228, s[2:3]
	v_cmp_gt_i32_e64 s[2:3], 11, v150
	v_cndmask_b32_e64 v37, v37, v228, s[46:47]
	v_cmp_gt_i32_e64 s[46:47], 16, v150
	v_cndmask_b32_e64 v38, v38, v228, vcc
	v_cmp_gt_i32_e64 vcc, 17, v150
	v_cndmask_b32_e64 v39, v39, v228, s[2:3]
	v_cmp_gt_i32_e64 s[2:3], 18, v150
	v_cndmask_b32_e64 v40, v40, v228, s[46:47]
	v_cmp_gt_i32_e64 s[46:47], 19, v150
	v_cndmask_b32_e64 v41, v41, v228, vcc
	v_cmp_gt_i32_e64 vcc, 24, v150
	v_cndmask_b32_e64 v42, v42, v228, s[2:3]
	v_cmp_gt_i32_e64 s[2:3], 25, v150
	v_cndmask_b32_e64 v43, v43, v228, s[46:47]
	v_cmp_gt_i32_e64 s[46:47], 26, v150
	v_cndmask_b32_e64 v44, v44, v228, vcc
	v_cmp_gt_i32_e64 vcc, 27, v150
	v_cndmask_b32_e64 v45, v45, v228, s[2:3]
	v_cndmask_b32_e64 v46, v46, v228, s[46:47]
	v_cndmask_b32_e64 v47, v47, v228, vcc
	v_max3_f32 v222, v32, v33, v34
	v_max3_f32 v222, v222, v35, v36
	v_max3_f32 v222, v222, v37, v38
	v_max3_f32 v222, v222, v39, v40
	v_max3_f32 v222, v222, v41, v42
	v_max3_f32 v222, v222, v43, v44
	v_max3_f32 v222, v222, v45, v46
	v_max_f32_e32 v222, v222, v47
	ds_bpermute_b32 v183, v151, v222
	s_waitcnt lgkmcnt(0)
	v_max_f32_e32 v183, v183, v183
	v_max_f32_e32 v182, v222, v183
	v_sub_f32_e32 v182, v182, v161
	v_add_f32_e32 v183, 0x40c00000, v164
	v_cmp_gt_f32_e32 vcc, v182, v183
	s_cbranch_vccz .Lfox_b1d0_pv
	v_max_f32_e32 v182, v182, v182
	v_max_f32_e32 v183, v164, v164
	v_max_f32_e32 v182, v183, v182
	v_sub_f32_e32 v164, v164, v182
	v_exp_f32_e32 v164, v164
	s_nop 0
	v_mul_f32_e32 v163, v163, v164
	v_pk_mul_f32 v[30:31], v[30:31], v[164:165] op_sel_hi:[1,0]
	v_pk_mul_f32 v[28:29], v[28:29], v[164:165] op_sel_hi:[1,0]
	v_pk_mul_f32 v[26:27], v[26:27], v[164:165] op_sel_hi:[1,0]
	v_pk_mul_f32 v[24:25], v[24:25], v[164:165] op_sel_hi:[1,0]
	v_pk_mul_f32 v[22:23], v[22:23], v[164:165] op_sel_hi:[1,0]
	v_pk_mul_f32 v[20:21], v[20:21], v[164:165] op_sel_hi:[1,0]
	v_pk_mul_f32 v[18:19], v[18:19], v[164:165] op_sel_hi:[1,0]
	v_pk_mul_f32 v[16:17], v[16:17], v[164:165] op_sel_hi:[1,0]
	v_pk_mul_f32 v[14:15], v[14:15], v[164:165] op_sel_hi:[1,0]
	v_pk_mul_f32 v[12:13], v[12:13], v[164:165] op_sel_hi:[1,0]
	v_pk_mul_f32 v[10:11], v[10:11], v[164:165] op_sel_hi:[1,0]
	v_pk_mul_f32 v[8:9], v[8:9], v[164:165] op_sel_hi:[1,0]
	v_pk_mul_f32 v[6:7], v[6:7], v[164:165] op_sel_hi:[1,0]
	v_pk_mul_f32 v[4:5], v[4:5], v[164:165] op_sel_hi:[1,0]
	v_pk_mul_f32 v[2:3], v[2:3], v[164:165] op_sel_hi:[1,0]
	v_pk_mul_f32 v[0:1], v[0:1], v[164:165] op_sel_hi:[1,0]
	v_mov_b32_e32 v164, v182
.Lfox_b1d0_pv:
	v_sub_f32_e64 v222, -v161, v164
	v_add_f32_e32 v32, v32, v222
	v_add_f32_e32 v33, v33, v222
	v_add_f32_e32 v34, v34, v222
	v_add_f32_e32 v35, v35, v222
	v_add_f32_e32 v36, v36, v222
	v_add_f32_e32 v37, v37, v222
	v_add_f32_e32 v38, v38, v222
	v_add_f32_e32 v39, v39, v222
	v_exp_f32_e32 v32, v32
	v_exp_f32_e32 v33, v33
	v_exp_f32_e32 v34, v34
	v_exp_f32_e32 v35, v35
	v_exp_f32_e32 v36, v36
	v_exp_f32_e32 v37, v37
	v_exp_f32_e32 v38, v38
	v_exp_f32_e32 v39, v39
	v_add_f32_e32 v182, v32, v33
	v_add_f32_e32 v183, v34, v35
	v_add_f32_e32 v182, v182, v36
	v_add_f32_e32 v183, v183, v37
	v_add_f32_e32 v182, v182, v38
	v_add_f32_e32 v183, v183, v39
	v_cvt_pk_bf16_f32 v32, v32, v33
	v_cvt_pk_bf16_f32 v33, v34, v35
	v_cvt_pk_bf16_f32 v34, v36, v37
	v_cvt_pk_bf16_f32 v35, v38, v39
	s_nop 1
	v_mfma_f32_32x32x16_bf16 v[16:31], v[202:205], v[32:35], v[16:31]
	v_add_f32_e32 v40, v40, v222
	v_add_f32_e32 v41, v41, v222
	v_add_f32_e32 v42, v42, v222
	v_add_f32_e32 v43, v43, v222
	v_add_f32_e32 v44, v44, v222
	v_add_f32_e32 v45, v45, v222
	v_add_f32_e32 v46, v46, v222
	v_add_f32_e32 v47, v47, v222
	v_exp_f32_e32 v40, v40
	v_exp_f32_e32 v41, v41
	v_exp_f32_e32 v42, v42
	v_exp_f32_e32 v43, v43
	v_exp_f32_e32 v44, v44
	v_exp_f32_e32 v45, v45
	v_exp_f32_e32 v46, v46
	v_exp_f32_e32 v47, v47
	v_mfma_f32_32x32x16_bf16 v[0:15], v[206:209], v[32:35], v[0:15]
	v_add_f32_e32 v182, v182, v40
	v_add_f32_e32 v183, v183, v41
	v_add_f32_e32 v182, v182, v42
	v_add_f32_e32 v183, v183, v43
	v_add_f32_e32 v182, v182, v44
	v_add_f32_e32 v183, v183, v45
	v_add_f32_e32 v182, v182, v46
	v_add_f32_e32 v183, v183, v47
	v_cvt_pk_bf16_f32 v40, v40, v41
	v_cvt_pk_bf16_f32 v41, v42, v43
	v_cvt_pk_bf16_f32 v42, v44, v45
	v_cvt_pk_bf16_f32 v43, v46, v47
	s_nop 1
	v_mfma_f32_32x32x16_bf16 v[16:31], v[210:213], v[40:43], v[16:31]
	v_mfma_f32_32x32x16_bf16 v[0:15], v[214:217], v[40:43], v[0:15]
	v_add_f32_e32 v163, v163, v182
	v_add_f32_e32 v163, v163, v183
	s_branch .Lfox_band_done
.Lfox_b1d1:
	ds_read_b128 v[32:35], v179 offset:512
	ds_read_b128 v[36:39], v179 offset:544
	ds_read_b128 v[40:43], v179 offset:576
	ds_read_b128 v[44:47], v179 offset:608
	ds_read_b128 v[48:51], v175 offset:32768
	ds_read_b128 v[52:55], v176 offset:32768
	ds_read_b128 v[56:59], v177 offset:32768
	ds_read_b128 v[60:63], v178 offset:32768
	ds_read_b128 v[80:83], v179 offset:640
	ds_read_b128 v[84:87], v179 offset:672
	ds_read_b128 v[88:91], v179 offset:704
	ds_read_b128 v[92:95], v179 offset:736
	s_waitcnt lgkmcnt(7)
	v_mfma_f32_32x32x16_bf16 v[32:47], v[48:51], v[96:99], v[32:47]
	ds_read_b128 v[64:67], v175 offset:36864
	s_waitcnt lgkmcnt(7)
	v_mfma_f32_32x32x16_bf16 v[32:47], v[52:55], v[100:103], v[32:47]
	ds_read_b128 v[68:71], v176 offset:36864
	s_waitcnt lgkmcnt(7)
	v_mfma_f32_32x32x16_bf16 v[32:47], v[56:59], v[104:107], v[32:47]
	ds_read_b128 v[72:75], v177 offset:36864
	s_waitcnt lgkmcnt(7)
	v_mfma_f32_32x32x16_bf16 v[32:47], v[60:63], v[108:111], v[32:47]
	ds_read_b128 v[76:79], v178 offset:36864
	s_waitcnt lgkmcnt(3)
	v_mfma_f32_32x32x16_bf16 v[80:95], v[64:67], v[96:99], v[80:95]
	s_waitcnt lgkmcnt(2)
	v_mfma_f32_32x32x16_bf16 v[80:95], v[68:71], v[100:103], v[80:95]
	s_waitcnt lgkmcnt(1)
	v_mfma_f32_32x32x16_bf16 v[80:95], v[72:75], v[104:107], v[80:95]
	s_waitcnt lgkmcnt(0)
	v_mfma_f32_32x32x16_bf16 v[80:95], v[76:79], v[108:111], v[80:95]
	v_add_u32_e32 v218, 0x12000, v181
	ds_read_b64_tr_b16 v[202:203], v218 offset:0
	ds_read_b64_tr_b16 v[204:205], v218 offset:1536
	ds_read_b64_tr_b16 v[206:207], v218 offset:64
	ds_read_b64_tr_b16 v[208:209], v218 offset:1600
	ds_read_b64_tr_b16 v[210:211], v218 offset:3072
	ds_read_b64_tr_b16 v[212:213], v218 offset:4608
	ds_read_b64_tr_b16 v[214:215], v218 offset:3136
	ds_read_b64_tr_b16 v[216:217], v218 offset:4672
	v_max3_f32 v222, v32, v33, v34
	v_max3_f32 v222, v222, v35, v36
	v_max3_f32 v222, v222, v37, v38
	v_max3_f32 v222, v222, v39, v40
	v_max3_f32 v222, v222, v41, v42
	v_max3_f32 v222, v222, v43, v44
	v_max3_f32 v222, v222, v45, v46
	v_cmp_gt_i32_e64 vcc, 0, v150
	v_cmp_gt_i32_e64 s[2:3], 1, v150
	v_cmp_gt_i32_e64 s[46:47], 2, v150
	v_cndmask_b32_e64 v80, v80, v228, vcc
	v_cmp_gt_i32_e64 vcc, 3, v150
	v_cndmask_b32_e64 v81, v81, v228, s[2:3]
	v_cmp_gt_i32_e64 s[2:3], 8, v150
	v_cndmask_b32_e64 v82, v82, v228, s[46:47]
	v_cmp_gt_i32_e64 s[46:47], 9, v150
	v_cndmask_b32_e64 v83, v83, v228, vcc
	v_cmp_gt_i32_e64 vcc, 10, v150
	v_cndmask_b32_e64 v84, v84, v228, s[2:3]
	v_cmp_gt_i32_e64 s[2:3], 11, v150
	v_cndmask_b32_e64 v85, v85, v228, s[46:47]
	v_cmp_gt_i32_e64 s[46:47], 16, v150
	v_cndmask_b32_e64 v86, v86, v228, vcc
	v_cmp_gt_i32_e64 vcc, 17, v150
	v_cndmask_b32_e64 v87, v87, v228, s[2:3]
	v_cmp_gt_i32_e64 s[2:3], 18, v150
	v_cndmask_b32_e64 v88, v88, v228, s[46:47]
	v_cmp_gt_i32_e64 s[46:47], 19, v150
	v_cndmask_b32_e64 v89, v89, v228, vcc
	v_cmp_gt_i32_e64 vcc, 24, v150
	v_cndmask_b32_e64 v90, v90, v228, s[2:3]
	v_cmp_gt_i32_e64 s[2:3], 25, v150
	v_cndmask_b32_e64 v91, v91, v228, s[46:47]
	v_cmp_gt_i32_e64 s[46:47], 26, v150
	v_cndmask_b32_e64 v92, v92, v228, vcc
	v_cmp_gt_i32_e64 vcc, 27, v150
	v_cndmask_b32_e64 v93, v93, v228, s[2:3]
	v_cndmask_b32_e64 v94, v94, v228, s[46:47]
	v_cndmask_b32_e64 v95, v95, v228, vcc
	v_max3_f32 v222, v222, v47, v80
	v_max3_f32 v222, v222, v81, v82
	v_max3_f32 v222, v222, v83, v84
	v_max3_f32 v222, v222, v85, v86
	v_max3_f32 v222, v222, v87, v88
	v_max3_f32 v222, v222, v89, v90
	v_max3_f32 v222, v222, v91, v92
	v_max3_f32 v222, v222, v93, v94
	v_max_f32_e32 v222, v222, v95
	ds_bpermute_b32 v183, v151, v222
	s_waitcnt lgkmcnt(0)
	v_max_f32_e32 v183, v183, v183
	v_max_f32_e32 v182, v222, v183
	v_sub_f32_e32 v182, v182, v161
	v_add_f32_e32 v183, 0x40c00000, v164
	v_cmp_gt_f32_e32 vcc, v182, v183
	s_cbranch_vccz .Lfox_b1d1_pv
	v_max_f32_e32 v182, v182, v182
	v_max_f32_e32 v183, v164, v164
	v_max_f32_e32 v182, v183, v182
	v_sub_f32_e32 v164, v164, v182
	v_exp_f32_e32 v164, v164
	s_nop 0
	v_mul_f32_e32 v163, v163, v164
	v_pk_mul_f32 v[30:31], v[30:31], v[164:165] op_sel_hi:[1,0]
	v_pk_mul_f32 v[28:29], v[28:29], v[164:165] op_sel_hi:[1,0]
	v_pk_mul_f32 v[26:27], v[26:27], v[164:165] op_sel_hi:[1,0]
	v_pk_mul_f32 v[24:25], v[24:25], v[164:165] op_sel_hi:[1,0]
	v_pk_mul_f32 v[22:23], v[22:23], v[164:165] op_sel_hi:[1,0]
	v_pk_mul_f32 v[20:21], v[20:21], v[164:165] op_sel_hi:[1,0]
	v_pk_mul_f32 v[18:19], v[18:19], v[164:165] op_sel_hi:[1,0]
	v_pk_mul_f32 v[16:17], v[16:17], v[164:165] op_sel_hi:[1,0]
	v_pk_mul_f32 v[14:15], v[14:15], v[164:165] op_sel_hi:[1,0]
	v_pk_mul_f32 v[12:13], v[12:13], v[164:165] op_sel_hi:[1,0]
	v_pk_mul_f32 v[10:11], v[10:11], v[164:165] op_sel_hi:[1,0]
	v_pk_mul_f32 v[8:9], v[8:9], v[164:165] op_sel_hi:[1,0]
	v_pk_mul_f32 v[6:7], v[6:7], v[164:165] op_sel_hi:[1,0]
	v_pk_mul_f32 v[4:5], v[4:5], v[164:165] op_sel_hi:[1,0]
	v_pk_mul_f32 v[2:3], v[2:3], v[164:165] op_sel_hi:[1,0]
	v_pk_mul_f32 v[0:1], v[0:1], v[164:165] op_sel_hi:[1,0]
	v_mov_b32_e32 v164, v182
.Lfox_b1d1_pv:
	v_sub_f32_e64 v222, -v161, v164
	v_add_f32_e32 v32, v32, v222
	v_add_f32_e32 v33, v33, v222
	v_add_f32_e32 v34, v34, v222
	v_add_f32_e32 v35, v35, v222
	v_add_f32_e32 v36, v36, v222
	v_add_f32_e32 v37, v37, v222
	v_add_f32_e32 v38, v38, v222
	v_add_f32_e32 v39, v39, v222
	v_exp_f32_e32 v32, v32
	v_exp_f32_e32 v33, v33
	v_exp_f32_e32 v34, v34
	v_exp_f32_e32 v35, v35
	v_exp_f32_e32 v36, v36
	v_exp_f32_e32 v37, v37
	v_exp_f32_e32 v38, v38
	v_exp_f32_e32 v39, v39
	v_add_f32_e32 v182, v32, v33
	v_add_f32_e32 v183, v34, v35
	v_add_f32_e32 v182, v182, v36
	v_add_f32_e32 v183, v183, v37
	v_add_f32_e32 v182, v182, v38
	v_add_f32_e32 v183, v183, v39
	v_cvt_pk_bf16_f32 v32, v32, v33
	v_cvt_pk_bf16_f32 v33, v34, v35
	v_cvt_pk_bf16_f32 v34, v36, v37
	v_cvt_pk_bf16_f32 v35, v38, v39
	s_nop 1
	v_mfma_f32_32x32x16_bf16 v[16:31], v[202:205], v[32:35], v[16:31]
	v_add_f32_e32 v40, v40, v222
	v_add_f32_e32 v41, v41, v222
	v_add_f32_e32 v42, v42, v222
	v_add_f32_e32 v43, v43, v222
	v_add_f32_e32 v44, v44, v222
	v_add_f32_e32 v45, v45, v222
	v_add_f32_e32 v46, v46, v222
	v_add_f32_e32 v47, v47, v222
	v_exp_f32_e32 v40, v40
	v_exp_f32_e32 v41, v41
	v_exp_f32_e32 v42, v42
	v_exp_f32_e32 v43, v43
	v_exp_f32_e32 v44, v44
	v_exp_f32_e32 v45, v45
	v_exp_f32_e32 v46, v46
	v_exp_f32_e32 v47, v47
	v_mfma_f32_32x32x16_bf16 v[0:15], v[206:209], v[32:35], v[0:15]
	ds_read_b64_tr_b16 v[202:203], v218 offset:6144
	ds_read_b64_tr_b16 v[204:205], v218 offset:7680
	ds_read_b64_tr_b16 v[206:207], v218 offset:6208
	ds_read_b64_tr_b16 v[208:209], v218 offset:7744
	v_add_f32_e32 v182, v182, v40
	v_add_f32_e32 v183, v183, v41
	v_add_f32_e32 v182, v182, v42
	v_add_f32_e32 v183, v183, v43
	v_add_f32_e32 v182, v182, v44
	v_add_f32_e32 v183, v183, v45
	v_add_f32_e32 v182, v182, v46
	v_add_f32_e32 v183, v183, v47
	v_cvt_pk_bf16_f32 v40, v40, v41
	v_cvt_pk_bf16_f32 v41, v42, v43
	v_cvt_pk_bf16_f32 v42, v44, v45
	v_cvt_pk_bf16_f32 v43, v46, v47
	s_nop 1
	v_mfma_f32_32x32x16_bf16 v[16:31], v[210:213], v[40:43], v[16:31]
	v_add_f32_e32 v80, v80, v222
	v_add_f32_e32 v81, v81, v222
	v_add_f32_e32 v82, v82, v222
	v_add_f32_e32 v83, v83, v222
	v_add_f32_e32 v84, v84, v222
	v_add_f32_e32 v85, v85, v222
	v_add_f32_e32 v86, v86, v222
	v_add_f32_e32 v87, v87, v222
	v_exp_f32_e32 v80, v80
	v_exp_f32_e32 v81, v81
	v_exp_f32_e32 v82, v82
	v_exp_f32_e32 v83, v83
	v_exp_f32_e32 v84, v84
	v_exp_f32_e32 v85, v85
	v_exp_f32_e32 v86, v86
	v_exp_f32_e32 v87, v87
	v_mfma_f32_32x32x16_bf16 v[0:15], v[214:217], v[40:43], v[0:15]
	ds_read_b64_tr_b16 v[210:211], v218 offset:9216
	ds_read_b64_tr_b16 v[212:213], v218 offset:10752
	ds_read_b64_tr_b16 v[214:215], v218 offset:9280
	ds_read_b64_tr_b16 v[216:217], v218 offset:10816
	v_add_f32_e32 v182, v182, v80
	v_add_f32_e32 v183, v183, v81
	v_add_f32_e32 v182, v182, v82
	v_add_f32_e32 v183, v183, v83
	v_add_f32_e32 v182, v182, v84
	v_add_f32_e32 v183, v183, v85
	v_add_f32_e32 v182, v182, v86
	v_add_f32_e32 v183, v183, v87
	v_cvt_pk_bf16_f32 v80, v80, v81
	v_cvt_pk_bf16_f32 v81, v82, v83
	v_cvt_pk_bf16_f32 v82, v84, v85
	v_cvt_pk_bf16_f32 v83, v86, v87
	s_waitcnt lgkmcnt(6)
	s_nop 0
	v_mfma_f32_32x32x16_bf16 v[16:31], v[202:205], v[80:83], v[16:31]
	v_add_f32_e32 v88, v88, v222
	v_add_f32_e32 v89, v89, v222
	v_add_f32_e32 v90, v90, v222
	v_add_f32_e32 v91, v91, v222
	v_add_f32_e32 v92, v92, v222
	v_add_f32_e32 v93, v93, v222
	v_add_f32_e32 v94, v94, v222
	v_add_f32_e32 v95, v95, v222
	v_exp_f32_e32 v88, v88
	v_exp_f32_e32 v89, v89
	v_exp_f32_e32 v90, v90
	v_exp_f32_e32 v91, v91
	v_exp_f32_e32 v92, v92
	v_exp_f32_e32 v93, v93
	v_exp_f32_e32 v94, v94
	v_exp_f32_e32 v95, v95
	s_waitcnt lgkmcnt(4)
	v_mfma_f32_32x32x16_bf16 v[0:15], v[206:209], v[80:83], v[0:15]
	v_add_f32_e32 v182, v182, v88
	v_add_f32_e32 v183, v183, v89
	v_add_f32_e32 v182, v182, v90
	v_add_f32_e32 v183, v183, v91
	v_add_f32_e32 v182, v182, v92
	v_add_f32_e32 v183, v183, v93
	v_add_f32_e32 v182, v182, v94
	v_add_f32_e32 v183, v183, v95
	v_cvt_pk_bf16_f32 v88, v88, v89
	v_cvt_pk_bf16_f32 v89, v90, v91
	v_cvt_pk_bf16_f32 v90, v92, v93
	v_cvt_pk_bf16_f32 v91, v94, v95
	s_waitcnt lgkmcnt(2)
	s_nop 0
	v_mfma_f32_32x32x16_bf16 v[16:31], v[210:213], v[88:91], v[16:31]
	s_waitcnt lgkmcnt(0)
	v_mfma_f32_32x32x16_bf16 v[0:15], v[214:217], v[88:91], v[0:15]
	v_add_f32_e32 v163, v163, v182
	v_add_f32_e32 v163, v163, v183
	s_branch .Lfox_band_done
.Lfox_b1d2:
	ds_read_b128 v[32:35], v179 offset:512
	ds_read_b128 v[36:39], v179 offset:544
	ds_read_b128 v[40:43], v179 offset:576
	ds_read_b128 v[44:47], v179 offset:608
	ds_read_b128 v[48:51], v175 offset:32768
	ds_read_b128 v[52:55], v176 offset:32768
	ds_read_b128 v[56:59], v177 offset:32768
	ds_read_b128 v[60:63], v178 offset:32768
	ds_read_b128 v[80:83], v179 offset:640
	ds_read_b128 v[84:87], v179 offset:672
	ds_read_b128 v[88:91], v179 offset:704
	ds_read_b128 v[92:95], v179 offset:736
	s_waitcnt lgkmcnt(7)
	v_mfma_f32_32x32x16_bf16 v[32:47], v[48:51], v[96:99], v[32:47]
	ds_read_b128 v[64:67], v175 offset:36864
	s_waitcnt lgkmcnt(7)
	v_mfma_f32_32x32x16_bf16 v[32:47], v[52:55], v[100:103], v[32:47]
	ds_read_b128 v[68:71], v176 offset:36864
	s_waitcnt lgkmcnt(7)
	v_mfma_f32_32x32x16_bf16 v[32:47], v[56:59], v[104:107], v[32:47]
	ds_read_b128 v[72:75], v177 offset:36864
	s_waitcnt lgkmcnt(7)
	v_mfma_f32_32x32x16_bf16 v[32:47], v[60:63], v[108:111], v[32:47]
	ds_read_b128 v[76:79], v178 offset:36864
	ds_read_b128 v[48:51], v179 offset:768
	ds_read_b128 v[52:55], v179 offset:800
	ds_read_b128 v[56:59], v179 offset:832
	ds_read_b128 v[60:63], v179 offset:864
	s_waitcnt lgkmcnt(7)
	v_mfma_f32_32x32x16_bf16 v[80:95], v[64:67], v[96:99], v[80:95]
	ds_read_b128 v[202:205], v175 offset:40960
	s_waitcnt lgkmcnt(7)
	v_mfma_f32_32x32x16_bf16 v[80:95], v[68:71], v[100:103], v[80:95]
	ds_read_b128 v[206:209], v176 offset:40960
	s_waitcnt lgkmcnt(7)
	v_mfma_f32_32x32x16_bf16 v[80:95], v[72:75], v[104:107], v[80:95]
	ds_read_b128 v[210:213], v177 offset:40960
	s_waitcnt lgkmcnt(7)
	v_mfma_f32_32x32x16_bf16 v[80:95], v[76:79], v[108:111], v[80:95]
	ds_read_b128 v[214:217], v178 offset:40960
	v_max3_f32 v222, v32, v33, v34
	v_max3_f32 v222, v222, v35, v36
	v_max3_f32 v222, v222, v37, v38
	v_max3_f32 v222, v222, v39, v40
	v_max3_f32 v222, v222, v41, v42
	v_max3_f32 v222, v222, v43, v44
	v_max3_f32 v222, v222, v45, v46
	s_waitcnt lgkmcnt(3)
	v_mfma_f32_32x32x16_bf16 v[48:63], v[202:205], v[96:99], v[48:63]
	s_waitcnt lgkmcnt(2)
	v_mfma_f32_32x32x16_bf16 v[48:63], v[206:209], v[100:103], v[48:63]
	s_waitcnt lgkmcnt(1)
	v_mfma_f32_32x32x16_bf16 v[48:63], v[210:213], v[104:107], v[48:63]
	s_waitcnt lgkmcnt(0)
	v_mfma_f32_32x32x16_bf16 v[48:63], v[214:217], v[108:111], v[48:63]
	v_max3_f32 v222, v222, v47, v80
	v_max3_f32 v222, v222, v81, v82
	v_max3_f32 v222, v222, v83, v84
	v_max3_f32 v222, v222, v85, v86
	v_max3_f32 v222, v222, v87, v88
	v_max3_f32 v222, v222, v89, v90
	v_max3_f32 v222, v222, v91, v92
	v_max3_f32 v222, v222, v93, v94
	v_add_u32_e32 v218, 0x12000, v181
	ds_read_b64_tr_b16 v[202:203], v218 offset:0
	ds_read_b64_tr_b16 v[204:205], v218 offset:1536
	ds_read_b64_tr_b16 v[206:207], v218 offset:64
	ds_read_b64_tr_b16 v[208:209], v218 offset:1600
	ds_read_b64_tr_b16 v[210:211], v218 offset:3072
	ds_read_b64_tr_b16 v[212:213], v218 offset:4608
	ds_read_b64_tr_b16 v[214:215], v218 offset:3136
	ds_read_b64_tr_b16 v[216:217], v218 offset:4672
	v_cmp_gt_i32_e64 vcc, 0, v150
	v_cmp_gt_i32_e64 s[2:3], 1, v150
	v_cmp_gt_i32_e64 s[46:47], 2, v150
	v_cndmask_b32_e64 v48, v48, v228, vcc
	v_cmp_gt_i32_e64 vcc, 3, v150
	v_cndmask_b32_e64 v49, v49, v228, s[2:3]
	v_cmp_gt_i32_e64 s[2:3], 8, v150
	v_cndmask_b32_e64 v50, v50, v228, s[46:47]
	v_cmp_gt_i32_e64 s[46:47], 9, v150
	v_cndmask_b32_e64 v51, v51, v228, vcc
	v_cmp_gt_i32_e64 vcc, 10, v150
	v_cndmask_b32_e64 v52, v52, v228, s[2:3]
	v_cmp_gt_i32_e64 s[2:3], 11, v150
	v_cndmask_b32_e64 v53, v53, v228, s[46:47]
	v_cmp_gt_i32_e64 s[46:47], 16, v150
	v_cndmask_b32_e64 v54, v54, v228, vcc
	v_cmp_gt_i32_e64 vcc, 17, v150
	v_cndmask_b32_e64 v55, v55, v228, s[2:3]
	v_cmp_gt_i32_e64 s[2:3], 18, v150
	v_cndmask_b32_e64 v56, v56, v228, s[46:47]
	v_cmp_gt_i32_e64 s[46:47], 19, v150
	v_cndmask_b32_e64 v57, v57, v228, vcc
	v_cmp_gt_i32_e64 vcc, 24, v150
	v_cndmask_b32_e64 v58, v58, v228, s[2:3]
	v_cmp_gt_i32_e64 s[2:3], 25, v150
	v_cndmask_b32_e64 v59, v59, v228, s[46:47]
	v_cmp_gt_i32_e64 s[46:47], 26, v150
	v_cndmask_b32_e64 v60, v60, v228, vcc
	v_cmp_gt_i32_e64 vcc, 27, v150
	v_cndmask_b32_e64 v61, v61, v228, s[2:3]
	v_cndmask_b32_e64 v62, v62, v228, s[46:47]
	v_cndmask_b32_e64 v63, v63, v228, vcc
	v_max3_f32 v222, v222, v95, v48
	v_max3_f32 v222, v222, v49, v50
	v_max3_f32 v222, v222, v51, v52
	v_max3_f32 v222, v222, v53, v54
	v_max3_f32 v222, v222, v55, v56
	v_max3_f32 v222, v222, v57, v58
	v_max3_f32 v222, v222, v59, v60
	v_max3_f32 v222, v222, v61, v62
	v_max_f32_e32 v222, v222, v63
	ds_bpermute_b32 v183, v151, v222
	s_waitcnt lgkmcnt(0)
	v_max_f32_e32 v183, v183, v183
	v_max_f32_e32 v182, v222, v183
	v_sub_f32_e32 v182, v182, v161
	v_add_f32_e32 v183, 0x40c00000, v164
	v_cmp_gt_f32_e32 vcc, v182, v183
	s_cbranch_vccz .Lfox_b1d2_pv
	v_max_f32_e32 v182, v182, v182
	v_max_f32_e32 v183, v164, v164
	v_max_f32_e32 v182, v183, v182
	v_sub_f32_e32 v164, v164, v182
	v_exp_f32_e32 v164, v164
	s_nop 0
	v_mul_f32_e32 v163, v163, v164
	v_pk_mul_f32 v[30:31], v[30:31], v[164:165] op_sel_hi:[1,0]
	v_pk_mul_f32 v[28:29], v[28:29], v[164:165] op_sel_hi:[1,0]
	v_pk_mul_f32 v[26:27], v[26:27], v[164:165] op_sel_hi:[1,0]
	v_pk_mul_f32 v[24:25], v[24:25], v[164:165] op_sel_hi:[1,0]
	v_pk_mul_f32 v[22:23], v[22:23], v[164:165] op_sel_hi:[1,0]
	v_pk_mul_f32 v[20:21], v[20:21], v[164:165] op_sel_hi:[1,0]
	v_pk_mul_f32 v[18:19], v[18:19], v[164:165] op_sel_hi:[1,0]
	v_pk_mul_f32 v[16:17], v[16:17], v[164:165] op_sel_hi:[1,0]
	v_pk_mul_f32 v[14:15], v[14:15], v[164:165] op_sel_hi:[1,0]
	v_pk_mul_f32 v[12:13], v[12:13], v[164:165] op_sel_hi:[1,0]
	v_pk_mul_f32 v[10:11], v[10:11], v[164:165] op_sel_hi:[1,0]
	v_pk_mul_f32 v[8:9], v[8:9], v[164:165] op_sel_hi:[1,0]
	v_pk_mul_f32 v[6:7], v[6:7], v[164:165] op_sel_hi:[1,0]
	v_pk_mul_f32 v[4:5], v[4:5], v[164:165] op_sel_hi:[1,0]
	v_pk_mul_f32 v[2:3], v[2:3], v[164:165] op_sel_hi:[1,0]
	v_pk_mul_f32 v[0:1], v[0:1], v[164:165] op_sel_hi:[1,0]
	v_mov_b32_e32 v164, v182
.Lfox_b1d2_pv:
	v_sub_f32_e64 v222, -v161, v164
	v_add_f32_e32 v32, v32, v222
	v_add_f32_e32 v33, v33, v222
	v_add_f32_e32 v34, v34, v222
	v_add_f32_e32 v35, v35, v222
	v_add_f32_e32 v36, v36, v222
	v_add_f32_e32 v37, v37, v222
	v_add_f32_e32 v38, v38, v222
	v_add_f32_e32 v39, v39, v222
	v_exp_f32_e32 v32, v32
	v_exp_f32_e32 v33, v33
	v_exp_f32_e32 v34, v34
	v_exp_f32_e32 v35, v35
	v_exp_f32_e32 v36, v36
	v_exp_f32_e32 v37, v37
	v_exp_f32_e32 v38, v38
	v_exp_f32_e32 v39, v39
	v_add_f32_e32 v182, v32, v33
	v_add_f32_e32 v183, v34, v35
	v_add_f32_e32 v182, v182, v36
	v_add_f32_e32 v183, v183, v37
	v_add_f32_e32 v182, v182, v38
	v_add_f32_e32 v183, v183, v39
	v_cvt_pk_bf16_f32 v32, v32, v33
	v_cvt_pk_bf16_f32 v33, v34, v35
	v_cvt_pk_bf16_f32 v34, v36, v37
	v_cvt_pk_bf16_f32 v35, v38, v39
	s_nop 1
	v_mfma_f32_32x32x16_bf16 v[16:31], v[202:205], v[32:35], v[16:31]
	v_add_f32_e32 v40, v40, v222
	v_add_f32_e32 v41, v41, v222
	v_add_f32_e32 v42, v42, v222
	v_add_f32_e32 v43, v43, v222
	v_add_f32_e32 v44, v44, v222
	v_add_f32_e32 v45, v45, v222
	v_add_f32_e32 v46, v46, v222
	v_add_f32_e32 v47, v47, v222
	v_exp_f32_e32 v40, v40
	v_exp_f32_e32 v41, v41
	v_exp_f32_e32 v42, v42
	v_exp_f32_e32 v43, v43
	v_exp_f32_e32 v44, v44
	v_exp_f32_e32 v45, v45
	v_exp_f32_e32 v46, v46
	v_exp_f32_e32 v47, v47
	v_mfma_f32_32x32x16_bf16 v[0:15], v[206:209], v[32:35], v[0:15]
	ds_read_b64_tr_b16 v[202:203], v218 offset:6144
	ds_read_b64_tr_b16 v[204:205], v218 offset:7680
	ds_read_b64_tr_b16 v[206:207], v218 offset:6208
	ds_read_b64_tr_b16 v[208:209], v218 offset:7744
	v_add_f32_e32 v182, v182, v40
	v_add_f32_e32 v183, v183, v41
	v_add_f32_e32 v182, v182, v42
	v_add_f32_e32 v183, v183, v43
	v_add_f32_e32 v182, v182, v44
	v_add_f32_e32 v183, v183, v45
	v_add_f32_e32 v182, v182, v46
	v_add_f32_e32 v183, v183, v47
	v_cvt_pk_bf16_f32 v40, v40, v41
	v_cvt_pk_bf16_f32 v41, v42, v43
	v_cvt_pk_bf16_f32 v42, v44, v45
	v_cvt_pk_bf16_f32 v43, v46, v47
	s_nop 1
	v_mfma_f32_32x32x16_bf16 v[16:31], v[210:213], v[40:43], v[16:31]
	v_add_f32_e32 v80, v80, v222
	v_add_f32_e32 v81, v81, v222
	v_add_f32_e32 v82, v82, v222
	v_add_f32_e32 v83, v83, v222
	v_add_f32_e32 v84, v84, v222
	v_add_f32_e32 v85, v85, v222
	v_add_f32_e32 v86, v86, v222
	v_add_f32_e32 v87, v87, v222
	v_exp_f32_e32 v80, v80
	v_exp_f32_e32 v81, v81
	v_exp_f32_e32 v82, v82
	v_exp_f32_e32 v83, v83
	v_exp_f32_e32 v84, v84
	v_exp_f32_e32 v85, v85
	v_exp_f32_e32 v86, v86
	v_exp_f32_e32 v87, v87
	v_mfma_f32_32x32x16_bf16 v[0:15], v[214:217], v[40:43], v[0:15]
	ds_read_b64_tr_b16 v[210:211], v218 offset:9216
	ds_read_b64_tr_b16 v[212:213], v218 offset:10752
	ds_read_b64_tr_b16 v[214:215], v218 offset:9280
	ds_read_b64_tr_b16 v[216:217], v218 offset:10816
	v_add_f32_e32 v182, v182, v80
	v_add_f32_e32 v183, v183, v81
	v_add_f32_e32 v182, v182, v82
	v_add_f32_e32 v183, v183, v83
	v_add_f32_e32 v182, v182, v84
	v_add_f32_e32 v183, v183, v85
	v_add_f32_e32 v182, v182, v86
	v_add_f32_e32 v183, v183, v87
	v_cvt_pk_bf16_f32 v80, v80, v81
	v_cvt_pk_bf16_f32 v81, v82, v83
	v_cvt_pk_bf16_f32 v82, v84, v85
	v_cvt_pk_bf16_f32 v83, v86, v87
	s_waitcnt lgkmcnt(6)
	s_nop 0
	v_mfma_f32_32x32x16_bf16 v[16:31], v[202:205], v[80:83], v[16:31]
	v_add_f32_e32 v88, v88, v222
	v_add_f32_e32 v89, v89, v222
	v_add_f32_e32 v90, v90, v222
	v_add_f32_e32 v91, v91, v222
	v_add_f32_e32 v92, v92, v222
	v_add_f32_e32 v93, v93, v222
	v_add_f32_e32 v94, v94, v222
	v_add_f32_e32 v95, v95, v222
	v_exp_f32_e32 v88, v88
	v_exp_f32_e32 v89, v89
	v_exp_f32_e32 v90, v90
	v_exp_f32_e32 v91, v91
	v_exp_f32_e32 v92, v92
	v_exp_f32_e32 v93, v93
	v_exp_f32_e32 v94, v94
	v_exp_f32_e32 v95, v95
	s_waitcnt lgkmcnt(4)
	v_mfma_f32_32x32x16_bf16 v[0:15], v[206:209], v[80:83], v[0:15]
	ds_read_b64_tr_b16 v[202:203], v218 offset:12288
	ds_read_b64_tr_b16 v[204:205], v218 offset:13824
	ds_read_b64_tr_b16 v[206:207], v218 offset:12352
	ds_read_b64_tr_b16 v[208:209], v218 offset:13888
	v_add_f32_e32 v182, v182, v88
	v_add_f32_e32 v183, v183, v89
	v_add_f32_e32 v182, v182, v90
	v_add_f32_e32 v183, v183, v91
	v_add_f32_e32 v182, v182, v92
	v_add_f32_e32 v183, v183, v93
	v_add_f32_e32 v182, v182, v94
	v_add_f32_e32 v183, v183, v95
	v_cvt_pk_bf16_f32 v88, v88, v89
	v_cvt_pk_bf16_f32 v89, v90, v91
	v_cvt_pk_bf16_f32 v90, v92, v93
	v_cvt_pk_bf16_f32 v91, v94, v95
	s_waitcnt lgkmcnt(6)
	s_nop 0
	v_mfma_f32_32x32x16_bf16 v[16:31], v[210:213], v[88:91], v[16:31]
	v_add_f32_e32 v48, v48, v222
	v_add_f32_e32 v49, v49, v222
	v_add_f32_e32 v50, v50, v222
	v_add_f32_e32 v51, v51, v222
	v_add_f32_e32 v52, v52, v222
	v_add_f32_e32 v53, v53, v222
	v_add_f32_e32 v54, v54, v222
	v_add_f32_e32 v55, v55, v222
	v_exp_f32_e32 v48, v48
	v_exp_f32_e32 v49, v49
	v_exp_f32_e32 v50, v50
	v_exp_f32_e32 v51, v51
	v_exp_f32_e32 v52, v52
	v_exp_f32_e32 v53, v53
	v_exp_f32_e32 v54, v54
	v_exp_f32_e32 v55, v55
	s_waitcnt lgkmcnt(4)
	v_mfma_f32_32x32x16_bf16 v[0:15], v[214:217], v[88:91], v[0:15]
	ds_read_b64_tr_b16 v[210:211], v218 offset:15360
	ds_read_b64_tr_b16 v[212:213], v218 offset:16896
	ds_read_b64_tr_b16 v[214:215], v218 offset:15424
	ds_read_b64_tr_b16 v[216:217], v218 offset:16960
	v_add_f32_e32 v182, v182, v48
	v_add_f32_e32 v183, v183, v49
	v_add_f32_e32 v182, v182, v50
	v_add_f32_e32 v183, v183, v51
	v_add_f32_e32 v182, v182, v52
	v_add_f32_e32 v183, v183, v53
	v_add_f32_e32 v182, v182, v54
	v_add_f32_e32 v183, v183, v55
	v_cvt_pk_bf16_f32 v48, v48, v49
	v_cvt_pk_bf16_f32 v49, v50, v51
	v_cvt_pk_bf16_f32 v50, v52, v53
	v_cvt_pk_bf16_f32 v51, v54, v55
	s_waitcnt lgkmcnt(6)
	s_nop 0
	v_mfma_f32_32x32x16_bf16 v[16:31], v[202:205], v[48:51], v[16:31]
	v_add_f32_e32 v56, v56, v222
	v_add_f32_e32 v57, v57, v222
	v_add_f32_e32 v58, v58, v222
	v_add_f32_e32 v59, v59, v222
	v_add_f32_e32 v60, v60, v222
	v_add_f32_e32 v61, v61, v222
	v_add_f32_e32 v62, v62, v222
	v_add_f32_e32 v63, v63, v222
	v_exp_f32_e32 v56, v56
	v_exp_f32_e32 v57, v57
	v_exp_f32_e32 v58, v58
	v_exp_f32_e32 v59, v59
	v_exp_f32_e32 v60, v60
	v_exp_f32_e32 v61, v61
	v_exp_f32_e32 v62, v62
	v_exp_f32_e32 v63, v63
	s_waitcnt lgkmcnt(4)
	v_mfma_f32_32x32x16_bf16 v[0:15], v[206:209], v[48:51], v[0:15]
	v_add_f32_e32 v182, v182, v56
	v_add_f32_e32 v183, v183, v57
	v_add_f32_e32 v182, v182, v58
	v_add_f32_e32 v183, v183, v59
	v_add_f32_e32 v182, v182, v60
	v_add_f32_e32 v183, v183, v61
	v_add_f32_e32 v182, v182, v62
	v_add_f32_e32 v183, v183, v63
	v_cvt_pk_bf16_f32 v56, v56, v57
	v_cvt_pk_bf16_f32 v57, v58, v59
	v_cvt_pk_bf16_f32 v58, v60, v61
	v_cvt_pk_bf16_f32 v59, v62, v63
	s_waitcnt lgkmcnt(2)
	s_nop 0
	v_mfma_f32_32x32x16_bf16 v[16:31], v[210:213], v[56:59], v[16:31]
	s_waitcnt lgkmcnt(0)
	v_mfma_f32_32x32x16_bf16 v[0:15], v[214:217], v[56:59], v[0:15]
	v_add_f32_e32 v163, v163, v182
	v_add_f32_e32 v163, v163, v183
	s_branch .Lfox_band_done
.Lfox_b1d3:
	ds_read_b128 v[32:35], v179 offset:512
	ds_read_b128 v[36:39], v179 offset:544
	ds_read_b128 v[40:43], v179 offset:576
	ds_read_b128 v[44:47], v179 offset:608
	ds_read_b128 v[48:51], v175 offset:32768
	ds_read_b128 v[52:55], v176 offset:32768
	ds_read_b128 v[56:59], v177 offset:32768
	ds_read_b128 v[60:63], v178 offset:32768
	ds_read_b128 v[80:83], v179 offset:640
	ds_read_b128 v[84:87], v179 offset:672
	ds_read_b128 v[88:91], v179 offset:704
	ds_read_b128 v[92:95], v179 offset:736
	s_waitcnt lgkmcnt(7)
	v_mfma_f32_32x32x16_bf16 v[32:47], v[48:51], v[96:99], v[32:47]
	ds_read_b128 v[64:67], v175 offset:36864
	s_waitcnt lgkmcnt(7)
	v_mfma_f32_32x32x16_bf16 v[32:47], v[52:55], v[100:103], v[32:47]
	ds_read_b128 v[68:71], v176 offset:36864
	s_waitcnt lgkmcnt(7)
	v_mfma_f32_32x32x16_bf16 v[32:47], v[56:59], v[104:107], v[32:47]
	ds_read_b128 v[72:75], v177 offset:36864
	s_waitcnt lgkmcnt(7)
	v_mfma_f32_32x32x16_bf16 v[32:47], v[60:63], v[108:111], v[32:47]
	ds_read_b128 v[76:79], v178 offset:36864
	ds_read_b128 v[48:51], v179 offset:768
	ds_read_b128 v[52:55], v179 offset:800
	ds_read_b128 v[56:59], v179 offset:832
	ds_read_b128 v[60:63], v179 offset:864
	s_waitcnt lgkmcnt(7)
	v_mfma_f32_32x32x16_bf16 v[80:95], v[64:67], v[96:99], v[80:95]
	ds_read_b128 v[202:205], v175 offset:40960
	s_waitcnt lgkmcnt(7)
	v_mfma_f32_32x32x16_bf16 v[80:95], v[68:71], v[100:103], v[80:95]
	ds_read_b128 v[206:209], v176 offset:40960
	s_waitcnt lgkmcnt(7)
	v_mfma_f32_32x32x16_bf16 v[80:95], v[72:75], v[104:107], v[80:95]
	ds_read_b128 v[210:213], v177 offset:40960
	s_waitcnt lgkmcnt(7)
	v_mfma_f32_32x32x16_bf16 v[80:95], v[76:79], v[108:111], v[80:95]
	ds_read_b128 v[214:217], v178 offset:40960
	ds_read_b128 v[64:67], v179 offset:896
	ds_read_b128 v[68:71], v179 offset:928
	ds_read_b128 v[72:75], v179 offset:960
	ds_read_b128 v[76:79], v179 offset:992
	ds_read_b128 v[218:221], v175 offset:45056
	v_max3_f32 v222, v32, v33, v34
	v_max3_f32 v222, v222, v35, v36
	v_max3_f32 v222, v222, v37, v38
	v_max3_f32 v222, v222, v39, v40
	v_max3_f32 v222, v222, v41, v42
	v_max3_f32 v222, v222, v43, v44
	v_max3_f32 v222, v222, v45, v46
	s_waitcnt lgkmcnt(8)
	v_mfma_f32_32x32x16_bf16 v[48:63], v[202:205], v[96:99], v[48:63]
	ds_read_b128 v[202:205], v176 offset:45056
	s_waitcnt lgkmcnt(8)
	v_mfma_f32_32x32x16_bf16 v[48:63], v[206:209], v[100:103], v[48:63]
	ds_read_b128 v[206:209], v177 offset:45056
	s_waitcnt lgkmcnt(8)
	v_mfma_f32_32x32x16_bf16 v[48:63], v[210:213], v[104:107], v[48:63]
	ds_read_b128 v[210:213], v178 offset:45056
	s_waitcnt lgkmcnt(8)
	v_mfma_f32_32x32x16_bf16 v[48:63], v[214:217], v[108:111], v[48:63]
	v_max3_f32 v222, v222, v47, v80
	v_max3_f32 v222, v222, v81, v82
	v_max3_f32 v222, v222, v83, v84
	v_max3_f32 v222, v222, v85, v86
	v_max3_f32 v222, v222, v87, v88
	v_max3_f32 v222, v222, v89, v90
	v_max3_f32 v222, v222, v91, v92
	v_max3_f32 v222, v222, v93, v94
	s_waitcnt lgkmcnt(3)
	v_mfma_f32_32x32x16_bf16 v[64:79], v[218:221], v[96:99], v[64:79]
	s_waitcnt lgkmcnt(2)
	v_mfma_f32_32x32x16_bf16 v[64:79], v[202:205], v[100:103], v[64:79]
	s_waitcnt lgkmcnt(1)
	v_mfma_f32_32x32x16_bf16 v[64:79], v[206:209], v[104:107], v[64:79]
	s_waitcnt lgkmcnt(0)
	v_mfma_f32_32x32x16_bf16 v[64:79], v[210:213], v[108:111], v[64:79]
	v_add_u32_e32 v218, 0x12000, v181
	ds_read_b64_tr_b16 v[202:203], v218 offset:0
	ds_read_b64_tr_b16 v[204:205], v218 offset:1536
	ds_read_b64_tr_b16 v[206:207], v218 offset:64
	ds_read_b64_tr_b16 v[208:209], v218 offset:1600
	ds_read_b64_tr_b16 v[210:211], v218 offset:3072
	ds_read_b64_tr_b16 v[212:213], v218 offset:4608
	ds_read_b64_tr_b16 v[214:215], v218 offset:3136
	ds_read_b64_tr_b16 v[216:217], v218 offset:4672
	v_max3_f32 v222, v222, v95, v48
	v_max3_f32 v222, v222, v49, v50
	v_max3_f32 v222, v222, v51, v52
	v_max3_f32 v222, v222, v53, v54
	v_max3_f32 v222, v222, v55, v56
	v_max3_f32 v222, v222, v57, v58
	v_max3_f32 v222, v222, v59, v60
	v_max3_f32 v222, v222, v61, v62
	v_cmp_gt_i32_e64 vcc, 0, v150
	v_cmp_gt_i32_e64 s[2:3], 1, v150
	v_cmp_gt_i32_e64 s[46:47], 2, v150
	v_cndmask_b32_e64 v64, v64, v228, vcc
	v_cmp_gt_i32_e64 vcc, 3, v150
	v_cndmask_b32_e64 v65, v65, v228, s[2:3]
	v_cmp_gt_i32_e64 s[2:3], 8, v150
	v_cndmask_b32_e64 v66, v66, v228, s[46:47]
	v_cmp_gt_i32_e64 s[46:47], 9, v150
	v_cndmask_b32_e64 v67, v67, v228, vcc
	v_cmp_gt_i32_e64 vcc, 10, v150
	v_cndmask_b32_e64 v68, v68, v228, s[2:3]
	v_cmp_gt_i32_e64 s[2:3], 11, v150
	v_cndmask_b32_e64 v69, v69, v228, s[46:47]
	v_cmp_gt_i32_e64 s[46:47], 16, v150
	v_cndmask_b32_e64 v70, v70, v228, vcc
	v_cmp_gt_i32_e64 vcc, 17, v150
	v_cndmask_b32_e64 v71, v71, v228, s[2:3]
	v_cmp_gt_i32_e64 s[2:3], 18, v150
	v_cndmask_b32_e64 v72, v72, v228, s[46:47]
	v_cmp_gt_i32_e64 s[46:47], 19, v150
	v_cndmask_b32_e64 v73, v73, v228, vcc
	v_cmp_gt_i32_e64 vcc, 24, v150
	v_cndmask_b32_e64 v74, v74, v228, s[2:3]
	v_cmp_gt_i32_e64 s[2:3], 25, v150
	v_cndmask_b32_e64 v75, v75, v228, s[46:47]
	v_cmp_gt_i32_e64 s[46:47], 26, v150
	v_cndmask_b32_e64 v76, v76, v228, vcc
	v_cmp_gt_i32_e64 vcc, 27, v150
	v_cndmask_b32_e64 v77, v77, v228, s[2:3]
	v_cndmask_b32_e64 v78, v78, v228, s[46:47]
	v_cndmask_b32_e64 v79, v79, v228, vcc
	v_max3_f32 v222, v222, v63, v64
	v_max3_f32 v222, v222, v65, v66
	v_max3_f32 v222, v222, v67, v68
	v_max3_f32 v222, v222, v69, v70
	v_max3_f32 v222, v222, v71, v72
	v_max3_f32 v222, v222, v73, v74
	v_max3_f32 v222, v222, v75, v76
	v_max3_f32 v222, v222, v77, v78
	v_max_f32_e32 v222, v222, v79
	ds_bpermute_b32 v183, v151, v222
	s_waitcnt lgkmcnt(0)
	v_max_f32_e32 v183, v183, v183
	v_max_f32_e32 v182, v222, v183
	v_sub_f32_e32 v182, v182, v161
	v_add_f32_e32 v183, 0x40c00000, v164
	v_cmp_gt_f32_e32 vcc, v182, v183
	s_cbranch_vccz .Lfox_b1d3_pv
	v_max_f32_e32 v182, v182, v182
	v_max_f32_e32 v183, v164, v164
	v_max_f32_e32 v182, v183, v182
	v_sub_f32_e32 v164, v164, v182
	v_exp_f32_e32 v164, v164
	s_nop 0
	v_mul_f32_e32 v163, v163, v164
	v_pk_mul_f32 v[30:31], v[30:31], v[164:165] op_sel_hi:[1,0]
	v_pk_mul_f32 v[28:29], v[28:29], v[164:165] op_sel_hi:[1,0]
	v_pk_mul_f32 v[26:27], v[26:27], v[164:165] op_sel_hi:[1,0]
	v_pk_mul_f32 v[24:25], v[24:25], v[164:165] op_sel_hi:[1,0]
	v_pk_mul_f32 v[22:23], v[22:23], v[164:165] op_sel_hi:[1,0]
	v_pk_mul_f32 v[20:21], v[20:21], v[164:165] op_sel_hi:[1,0]
	v_pk_mul_f32 v[18:19], v[18:19], v[164:165] op_sel_hi:[1,0]
	v_pk_mul_f32 v[16:17], v[16:17], v[164:165] op_sel_hi:[1,0]
	v_pk_mul_f32 v[14:15], v[14:15], v[164:165] op_sel_hi:[1,0]
	v_pk_mul_f32 v[12:13], v[12:13], v[164:165] op_sel_hi:[1,0]
	v_pk_mul_f32 v[10:11], v[10:11], v[164:165] op_sel_hi:[1,0]
	v_pk_mul_f32 v[8:9], v[8:9], v[164:165] op_sel_hi:[1,0]
	v_pk_mul_f32 v[6:7], v[6:7], v[164:165] op_sel_hi:[1,0]
	v_pk_mul_f32 v[4:5], v[4:5], v[164:165] op_sel_hi:[1,0]
	v_pk_mul_f32 v[2:3], v[2:3], v[164:165] op_sel_hi:[1,0]
	v_pk_mul_f32 v[0:1], v[0:1], v[164:165] op_sel_hi:[1,0]
	v_mov_b32_e32 v164, v182
.Lfox_b1d3_pv:
	v_sub_f32_e64 v222, -v161, v164
	v_add_f32_e32 v32, v32, v222
	v_add_f32_e32 v33, v33, v222
	v_add_f32_e32 v34, v34, v222
	v_add_f32_e32 v35, v35, v222
	v_add_f32_e32 v36, v36, v222
	v_add_f32_e32 v37, v37, v222
	v_add_f32_e32 v38, v38, v222
	v_add_f32_e32 v39, v39, v222
	v_exp_f32_e32 v32, v32
	v_exp_f32_e32 v33, v33
	v_exp_f32_e32 v34, v34
	v_exp_f32_e32 v35, v35
	v_exp_f32_e32 v36, v36
	v_exp_f32_e32 v37, v37
	v_exp_f32_e32 v38, v38
	v_exp_f32_e32 v39, v39
	v_add_f32_e32 v182, v32, v33
	v_add_f32_e32 v183, v34, v35
	v_add_f32_e32 v182, v182, v36
	v_add_f32_e32 v183, v183, v37
	v_add_f32_e32 v182, v182, v38
	v_add_f32_e32 v183, v183, v39
	v_cvt_pk_bf16_f32 v32, v32, v33
	v_cvt_pk_bf16_f32 v33, v34, v35
	v_cvt_pk_bf16_f32 v34, v36, v37
	v_cvt_pk_bf16_f32 v35, v38, v39
	s_nop 1
	v_mfma_f32_32x32x16_bf16 v[16:31], v[202:205], v[32:35], v[16:31]
	v_add_f32_e32 v40, v40, v222
	v_add_f32_e32 v41, v41, v222
	v_add_f32_e32 v42, v42, v222
	v_add_f32_e32 v43, v43, v222
	v_add_f32_e32 v44, v44, v222
	v_add_f32_e32 v45, v45, v222
	v_add_f32_e32 v46, v46, v222
	v_add_f32_e32 v47, v47, v222
	v_exp_f32_e32 v40, v40
	v_exp_f32_e32 v41, v41
	v_exp_f32_e32 v42, v42
	v_exp_f32_e32 v43, v43
	v_exp_f32_e32 v44, v44
	v_exp_f32_e32 v45, v45
	v_exp_f32_e32 v46, v46
	v_exp_f32_e32 v47, v47
	v_mfma_f32_32x32x16_bf16 v[0:15], v[206:209], v[32:35], v[0:15]
	ds_read_b64_tr_b16 v[202:203], v218 offset:6144
	ds_read_b64_tr_b16 v[204:205], v218 offset:7680
	ds_read_b64_tr_b16 v[206:207], v218 offset:6208
	ds_read_b64_tr_b16 v[208:209], v218 offset:7744
	v_add_f32_e32 v182, v182, v40
	v_add_f32_e32 v183, v183, v41
	v_add_f32_e32 v182, v182, v42
	v_add_f32_e32 v183, v183, v43
	v_add_f32_e32 v182, v182, v44
	v_add_f32_e32 v183, v183, v45
	v_add_f32_e32 v182, v182, v46
	v_add_f32_e32 v183, v183, v47
	v_cvt_pk_bf16_f32 v40, v40, v41
	v_cvt_pk_bf16_f32 v41, v42, v43
	v_cvt_pk_bf16_f32 v42, v44, v45
	v_cvt_pk_bf16_f32 v43, v46, v47
	s_nop 1
	v_mfma_f32_32x32x16_bf16 v[16:31], v[210:213], v[40:43], v[16:31]
	v_add_f32_e32 v80, v80, v222
	v_add_f32_e32 v81, v81, v222
	v_add_f32_e32 v82, v82, v222
	v_add_f32_e32 v83, v83, v222
	v_add_f32_e32 v84, v84, v222
	v_add_f32_e32 v85, v85, v222
	v_add_f32_e32 v86, v86, v222
	v_add_f32_e32 v87, v87, v222
	v_exp_f32_e32 v80, v80
	v_exp_f32_e32 v81, v81
	v_exp_f32_e32 v82, v82
	v_exp_f32_e32 v83, v83
	v_exp_f32_e32 v84, v84
	v_exp_f32_e32 v85, v85
	v_exp_f32_e32 v86, v86
	v_exp_f32_e32 v87, v87
	v_mfma_f32_32x32x16_bf16 v[0:15], v[214:217], v[40:43], v[0:15]
	ds_read_b64_tr_b16 v[210:211], v218 offset:9216
	ds_read_b64_tr_b16 v[212:213], v218 offset:10752
	ds_read_b64_tr_b16 v[214:215], v218 offset:9280
	ds_read_b64_tr_b16 v[216:217], v218 offset:10816
	v_add_f32_e32 v182, v182, v80
	v_add_f32_e32 v183, v183, v81
	v_add_f32_e32 v182, v182, v82
	v_add_f32_e32 v183, v183, v83
	v_add_f32_e32 v182, v182, v84
	v_add_f32_e32 v183, v183, v85
	v_add_f32_e32 v182, v182, v86
	v_add_f32_e32 v183, v183, v87
	v_cvt_pk_bf16_f32 v80, v80, v81
	v_cvt_pk_bf16_f32 v81, v82, v83
	v_cvt_pk_bf16_f32 v82, v84, v85
	v_cvt_pk_bf16_f32 v83, v86, v87
	s_waitcnt lgkmcnt(6)
	s_nop 0
	v_mfma_f32_32x32x16_bf16 v[16:31], v[202:205], v[80:83], v[16:31]
	v_add_f32_e32 v88, v88, v222
	v_add_f32_e32 v89, v89, v222
	v_add_f32_e32 v90, v90, v222
	v_add_f32_e32 v91, v91, v222
	v_add_f32_e32 v92, v92, v222
	v_add_f32_e32 v93, v93, v222
	v_add_f32_e32 v94, v94, v222
	v_add_f32_e32 v95, v95, v222
	v_exp_f32_e32 v88, v88
	v_exp_f32_e32 v89, v89
	v_exp_f32_e32 v90, v90
	v_exp_f32_e32 v91, v91
	v_exp_f32_e32 v92, v92
	v_exp_f32_e32 v93, v93
	v_exp_f32_e32 v94, v94
	v_exp_f32_e32 v95, v95
	s_waitcnt lgkmcnt(4)
	v_mfma_f32_32x32x16_bf16 v[0:15], v[206:209], v[80:83], v[0:15]
	ds_read_b64_tr_b16 v[202:203], v218 offset:12288
	ds_read_b64_tr_b16 v[204:205], v218 offset:13824
	ds_read_b64_tr_b16 v[206:207], v218 offset:12352
	ds_read_b64_tr_b16 v[208:209], v218 offset:13888
	v_add_f32_e32 v182, v182, v88
	v_add_f32_e32 v183, v183, v89
	v_add_f32_e32 v182, v182, v90
	v_add_f32_e32 v183, v183, v91
	v_add_f32_e32 v182, v182, v92
	v_add_f32_e32 v183, v183, v93
	v_add_f32_e32 v182, v182, v94
	v_add_f32_e32 v183, v183, v95
	v_cvt_pk_bf16_f32 v88, v88, v89
	v_cvt_pk_bf16_f32 v89, v90, v91
	v_cvt_pk_bf16_f32 v90, v92, v93
	v_cvt_pk_bf16_f32 v91, v94, v95
	s_waitcnt lgkmcnt(6)
	s_nop 0
	v_mfma_f32_32x32x16_bf16 v[16:31], v[210:213], v[88:91], v[16:31]
	v_add_f32_e32 v48, v48, v222
	v_add_f32_e32 v49, v49, v222
	v_add_f32_e32 v50, v50, v222
	v_add_f32_e32 v51, v51, v222
	v_add_f32_e32 v52, v52, v222
	v_add_f32_e32 v53, v53, v222
	v_add_f32_e32 v54, v54, v222
	v_add_f32_e32 v55, v55, v222
	v_exp_f32_e32 v48, v48
	v_exp_f32_e32 v49, v49
	v_exp_f32_e32 v50, v50
	v_exp_f32_e32 v51, v51
	v_exp_f32_e32 v52, v52
	v_exp_f32_e32 v53, v53
	v_exp_f32_e32 v54, v54
	v_exp_f32_e32 v55, v55
	s_waitcnt lgkmcnt(4)
	v_mfma_f32_32x32x16_bf16 v[0:15], v[214:217], v[88:91], v[0:15]
	ds_read_b64_tr_b16 v[210:211], v218 offset:15360
	ds_read_b64_tr_b16 v[212:213], v218 offset:16896
	ds_read_b64_tr_b16 v[214:215], v218 offset:15424
	ds_read_b64_tr_b16 v[216:217], v218 offset:16960
	v_add_f32_e32 v182, v182, v48
	v_add_f32_e32 v183, v183, v49
	v_add_f32_e32 v182, v182, v50
	v_add_f32_e32 v183, v183, v51
	v_add_f32_e32 v182, v182, v52
	v_add_f32_e32 v183, v183, v53
	v_add_f32_e32 v182, v182, v54
	v_add_f32_e32 v183, v183, v55
	v_cvt_pk_bf16_f32 v48, v48, v49
	v_cvt_pk_bf16_f32 v49, v50, v51
	v_cvt_pk_bf16_f32 v50, v52, v53
	v_cvt_pk_bf16_f32 v51, v54, v55
	s_waitcnt lgkmcnt(6)
	s_nop 0
	v_mfma_f32_32x32x16_bf16 v[16:31], v[202:205], v[48:51], v[16:31]
	v_add_f32_e32 v56, v56, v222
	v_add_f32_e32 v57, v57, v222
	v_add_f32_e32 v58, v58, v222
	v_add_f32_e32 v59, v59, v222
	v_add_f32_e32 v60, v60, v222
	v_add_f32_e32 v61, v61, v222
	v_add_f32_e32 v62, v62, v222
	v_add_f32_e32 v63, v63, v222
	v_exp_f32_e32 v56, v56
	v_exp_f32_e32 v57, v57
	v_exp_f32_e32 v58, v58
	v_exp_f32_e32 v59, v59
	v_exp_f32_e32 v60, v60
	v_exp_f32_e32 v61, v61
	v_exp_f32_e32 v62, v62
	v_exp_f32_e32 v63, v63
	s_waitcnt lgkmcnt(4)
	v_mfma_f32_32x32x16_bf16 v[0:15], v[206:209], v[48:51], v[0:15]
	ds_read_b64_tr_b16 v[202:203], v218 offset:18432
	ds_read_b64_tr_b16 v[204:205], v218 offset:19968
	ds_read_b64_tr_b16 v[206:207], v218 offset:18496
	ds_read_b64_tr_b16 v[208:209], v218 offset:20032
	v_add_f32_e32 v182, v182, v56
	v_add_f32_e32 v183, v183, v57
	v_add_f32_e32 v182, v182, v58
	v_add_f32_e32 v183, v183, v59
	v_add_f32_e32 v182, v182, v60
	v_add_f32_e32 v183, v183, v61
	v_add_f32_e32 v182, v182, v62
	v_add_f32_e32 v183, v183, v63
	v_cvt_pk_bf16_f32 v56, v56, v57
	v_cvt_pk_bf16_f32 v57, v58, v59
	v_cvt_pk_bf16_f32 v58, v60, v61
	v_cvt_pk_bf16_f32 v59, v62, v63
	s_waitcnt lgkmcnt(6)
	s_nop 0
	v_mfma_f32_32x32x16_bf16 v[16:31], v[210:213], v[56:59], v[16:31]
	v_add_f32_e32 v64, v64, v222
	v_add_f32_e32 v65, v65, v222
	v_add_f32_e32 v66, v66, v222
	v_add_f32_e32 v67, v67, v222
	v_add_f32_e32 v68, v68, v222
	v_add_f32_e32 v69, v69, v222
	v_add_f32_e32 v70, v70, v222
	v_add_f32_e32 v71, v71, v222
	v_exp_f32_e32 v64, v64
	v_exp_f32_e32 v65, v65
	v_exp_f32_e32 v66, v66
	v_exp_f32_e32 v67, v67
	v_exp_f32_e32 v68, v68
	v_exp_f32_e32 v69, v69
	v_exp_f32_e32 v70, v70
	v_exp_f32_e32 v71, v71
	s_waitcnt lgkmcnt(4)
	v_mfma_f32_32x32x16_bf16 v[0:15], v[214:217], v[56:59], v[0:15]
	ds_read_b64_tr_b16 v[210:211], v218 offset:21504
	ds_read_b64_tr_b16 v[212:213], v218 offset:23040
	ds_read_b64_tr_b16 v[214:215], v218 offset:21568
	ds_read_b64_tr_b16 v[216:217], v218 offset:23104
	v_add_f32_e32 v182, v182, v64
	v_add_f32_e32 v183, v183, v65
	v_add_f32_e32 v182, v182, v66
	v_add_f32_e32 v183, v183, v67
	v_add_f32_e32 v182, v182, v68
	v_add_f32_e32 v183, v183, v69
	v_add_f32_e32 v182, v182, v70
	v_add_f32_e32 v183, v183, v71
	v_cvt_pk_bf16_f32 v64, v64, v65
	v_cvt_pk_bf16_f32 v65, v66, v67
	v_cvt_pk_bf16_f32 v66, v68, v69
	v_cvt_pk_bf16_f32 v67, v70, v71
	s_waitcnt lgkmcnt(6)
	s_nop 0
	v_mfma_f32_32x32x16_bf16 v[16:31], v[202:205], v[64:67], v[16:31]
	v_add_f32_e32 v72, v72, v222
	v_add_f32_e32 v73, v73, v222
	v_add_f32_e32 v74, v74, v222
	v_add_f32_e32 v75, v75, v222
	v_add_f32_e32 v76, v76, v222
	v_add_f32_e32 v77, v77, v222
	v_add_f32_e32 v78, v78, v222
	v_add_f32_e32 v79, v79, v222
	v_exp_f32_e32 v72, v72
	v_exp_f32_e32 v73, v73
	v_exp_f32_e32 v74, v74
	v_exp_f32_e32 v75, v75
	v_exp_f32_e32 v76, v76
	v_exp_f32_e32 v77, v77
	v_exp_f32_e32 v78, v78
	v_exp_f32_e32 v79, v79
	s_waitcnt lgkmcnt(4)
	v_mfma_f32_32x32x16_bf16 v[0:15], v[206:209], v[64:67], v[0:15]
	v_add_f32_e32 v182, v182, v72
	v_add_f32_e32 v183, v183, v73
	v_add_f32_e32 v182, v182, v74
	v_add_f32_e32 v183, v183, v75
	v_add_f32_e32 v182, v182, v76
	v_add_f32_e32 v183, v183, v77
	v_add_f32_e32 v182, v182, v78
	v_add_f32_e32 v183, v183, v79
	v_cvt_pk_bf16_f32 v72, v72, v73
	v_cvt_pk_bf16_f32 v73, v74, v75
	v_cvt_pk_bf16_f32 v74, v76, v77
	v_cvt_pk_bf16_f32 v75, v78, v79
	s_waitcnt lgkmcnt(2)
	s_nop 0
	v_mfma_f32_32x32x16_bf16 v[16:31], v[210:213], v[72:75], v[16:31]
	s_waitcnt lgkmcnt(0)
	v_mfma_f32_32x32x16_bf16 v[0:15], v[214:217], v[72:75], v[0:15]
	v_add_f32_e32 v163, v163, v182
	v_add_f32_e32 v163, v163, v183
	s_branch .Lfox_band_done
.Lfox_band_done:
	s_waitcnt lgkmcnt(0)
	s_barrier
	s_branch .LBB0_558
